# v26: v25 + in-proj epilogue head: row scales and first-half column maxima loaded at the top of the unit's K loop (dead regs, two counted waits +5); kinds 2/4/5/6 need no vmcnt(0) at the epilogue head
# baseline (speedup 1.0000x reference)
; #define G_STAGE_B(bufoff, gbase) do { G_GLDS((const char*)(gbase) + voffB0, (bufoff) + ldsw); G_GLDS((const char*)(gbase) + vstep64 + voffB0, (bufoff) + ldsw + 8192); } while (0)
; #define G_STAGE_AU(bufoff, gbase) do { G_GLDS((const char*)(gbase) + voffA0, (bufoff) + ldsw); G_GLDS((const char*)(gbase) + vstep64 + voffA0, (bufoff) + ldsw + 8192); } while (0)
; #define X_LDA(b, h) do { if constexpr (MODE == 2) G_LDA8(A8, b, h); else G_LDA(At, b, h); } while (0)
; #define X_LDB0(b, h) do { if constexpr (MODE == 2) G_LDB8(B08, b, h); else G_LDB(B0, b, h); } while (0)
; #define X_LDB1(b, h) do { if constexpr (MODE == 2) G_LDB8(B18, b, h); else G_LDB(B1, b, h); } while (0)
; #define X_MMA0(ai, bj) do { if constexpr (MODE == 2) G_MMA8(ai, bj, A8, B08); else G_MMA(ai, bj, At, B0); } while (0)
; #define X_MMA1(ai, bj) do { if constexpr (MODE == 2) G_MMA8(ai, bj, A8, B18); else G_MMA(ai, bj, At, B1); } while (0)
; #define G_WAIT_V(n) asm volatile("s_waitcnt vmcnt(" #n ")" ::: "memory")
;     template <int KIND>
;     __device__ __forceinline__ void run(const f32x4 (&acc)[2][2][4][2], const Unit& u, int wr, int wc, int fr, int fq) const {
;     ...
;         const float sa_lo = sa[u.pm * BM + wr * 64 + fr + 16 * fq], sa_hi = sa[u.pm * BM + HALF + wr * 64 + fr + 16 * fq];
; #pragma unroll
;         for (int bj = 0; bj < 2; ++bj) {
;             f32x2_t sc2[4], aux2[4];
; #pragma unroll
;             for (int j = 0; j < 4; ++j) {
;                 const float k0 = (KIND == 4) ? (0.125f * LOG2E / 127.0f) : (1.0f / 127.0f);
;                 sc2[j] = (f32x2_t){wmax[col0 + bj * HALF + 2 * j] * k0, wmax[col0 + bj * HALF + 2 * j + 1] * k0};
;     ...
;         for (int t = 0; t < nt; t += 2) {
;             const bool last = (t == nt - 2);
;             const char* a1 = cA + (size_t)(t + 1) * kstep;
;             const char* a2 = last ? nA : cA + (size_t)(t + 2) * kstep; const char* b2 = last ? nB : cB + (size_t)(t + 2) * kstep;
;             const char* a3 = a2 + kstep; const char* b3 = b2 + kstep;
;             X_LDB0(0, 0); X_LDB1(0, 1); G_SCHED; X_LDA(0, 0); G_STAGE_AU(G_SA(1, 1), a1 + hstep);
;             G_WAIT_V(8); G_WAIT_L(0); G_BAR; X_MMA0(0, 0); X_MMA1(0, 1); G_BAR; G_SCHED;
;             X_LDA(0, 1); G_STAGE_B(G_SB(0, 0), b2); G_STAGE_B(G_SB(0, 1), b2 + hstep); G_STAGE_AU(G_SA(0, 0), a2);
;             G_WAIT_V(8); G_WAIT_L(0); G_BAR; X_MMA0(1, 0); X_MMA1(1, 1); G_BAR; G_SCHED;
.Lmy_peel_inproj_203:
	v_lshl_add_u32 v244, s90, 8, v212
	v_or_b32_e32 v246, v244, v214
	v_ashrrev_i32_e32 v247, 31, v246
	v_lshl_add_u64 v[246:247], v[246:247], 2, s[46:47]
	global_load_dword v209, v[246:247], off
	v_lshl_add_u32 v246, s90, 8, v215
	v_ashrrev_i32_e32 v247, 31, v246
	v_lshl_add_u64 v[246:247], v[246:247], 2, s[46:47]
	global_load_dword v208, v[246:247], off
	v_lshl_or_b32 v246, s2, 8, v216
	v_ashrrev_i32_e32 v247, 31, v246
	v_lshl_add_u64 v[246:247], v[246:247], 2, s[48:49]
	global_load_dwordx2 v[236:237], v[246:247], off
	global_load_dwordx4 v[238:241], v[246:247], off offset:8
	global_load_dwordx2 v[242:243], v[246:247], off offset:24
	ds_read_b128 v[132:135], v217
	ds_read_b128 v[136:139], v217 offset:1024
	ds_read_b128 v[146:149], v217 offset:2048
	ds_read_b128 v[150:153], v217 offset:3072
	ds_read_b128 v[154:157], v218
	ds_read_b128 v[158:161], v218 offset:1024
	ds_read_b128 v[162:165], v218 offset:2048
	ds_read_b128 v[166:169], v218 offset:3072
	s_add_u32 s16, s0, 0xfffe0080
	s_addc_u32 s38, s1, -1
	s_cmp_eq_u32 s11, 4
	s_cselect_b32 s39, s3, s38
	s_cselect_b32 s38, s6, s16
	s_cselect_b32 s95, s7, s9
	s_cselect_b32 s94, s10, s8
	s_mov_b32 m0, s69
	v_lshl_add_u64 v[202:203], s[0:1], 0, v[144:145]
	ds_read_b128 v[170:173], v219
	ds_read_b128 v[174:177], v219 offset:1024
	ds_read_b128 v[178:181], v219 offset:2048
	ds_read_b128 v[182:185], v219 offset:3072
	ds_read_b128 v[186:189], v219 offset:4096
	ds_read_b128 v[190:193], v219 offset:5120
	ds_read_b128 v[194:197], v219 offset:6144
	ds_read_b128 v[198:201], v219 offset:7168
	global_load_lds_dwordx4 v[202:203], off
	v_lshl_add_u64 v[202:203], v[202:203], 0, s[20:21]
	s_mov_b32 m0, s72
	s_nop 0
	global_load_lds_dwordx4 v[202:203], off
	s_waitcnt vmcnt(13)
	s_waitcnt lgkmcnt(0)
	s_barrier
	s_setprio 1
	s_waitcnt lgkmcnt(0)
	v_mfma_i32_16x16x64_i8 v[128:131], v[132:135], v[170:173], 0
	v_mfma_i32_16x16x64_i8 v[124:127], v[146:149], v[170:173], 0
	v_mfma_i32_16x16x64_i8 v[120:123], v[132:135], v[178:181], 0
	v_mfma_i32_16x16x64_i8 v[116:119], v[146:149], v[178:181], 0
	v_mfma_i32_16x16x64_i8 v[112:115], v[132:135], v[186:189], 0
	v_mfma_i32_16x16x64_i8 v[108:111], v[146:149], v[186:189], 0
	v_mfma_i32_16x16x64_i8 v[104:107], v[132:135], v[194:197], 0
	v_mfma_i32_16x16x64_i8 v[100:103], v[146:149], v[194:197], 0
	v_mfma_i32_16x16x64_i8 v[128:131], v[136:139], v[174:177], v[128:131]
	v_mfma_i32_16x16x64_i8 v[124:127], v[150:153], v[174:177], v[124:127]
	v_mfma_i32_16x16x64_i8 v[120:123], v[136:139], v[182:185], v[120:123]
	v_mfma_i32_16x16x64_i8 v[116:119], v[150:153], v[182:185], v[116:119]
	v_mfma_i32_16x16x64_i8 v[112:115], v[136:139], v[190:193], v[112:115]
	v_mfma_i32_16x16x64_i8 v[108:111], v[150:153], v[190:193], v[108:111]
	v_mfma_i32_16x16x64_i8 v[104:107], v[136:139], v[198:201], v[104:107]
	v_mfma_i32_16x16x64_i8 v[100:103], v[150:153], v[198:201], v[100:103]
	s_setprio 0
	s_setprio 1
	v_mfma_i32_16x16x64_i8 v[62:65], v[154:157], v[170:173], 0
	v_mfma_i32_16x16x64_i8 v[58:61], v[162:165], v[170:173], 0
	v_mfma_i32_16x16x64_i8 v[54:57], v[154:157], v[178:181], 0
	v_mfma_i32_16x16x64_i8 v[50:53], v[162:165], v[178:181], 0
	v_mfma_i32_16x16x64_i8 v[46:49], v[154:157], v[186:189], 0
	v_mfma_i32_16x16x64_i8 v[42:45], v[162:165], v[186:189], 0
	v_mfma_i32_16x16x64_i8 v[38:41], v[154:157], v[194:197], 0
	v_mfma_i32_16x16x64_i8 v[34:37], v[162:165], v[194:197], 0
	v_mfma_i32_16x16x64_i8 v[62:65], v[158:161], v[174:177], v[62:65]
	v_mfma_i32_16x16x64_i8 v[58:61], v[166:169], v[174:177], v[58:61]
	v_mfma_i32_16x16x64_i8 v[54:57], v[158:161], v[182:185], v[54:57]
	v_mfma_i32_16x16x64_i8 v[50:53], v[166:169], v[182:185], v[50:53]
	v_mfma_i32_16x16x64_i8 v[46:49], v[158:161], v[190:193], v[46:49]
	v_mfma_i32_16x16x64_i8 v[42:45], v[166:169], v[190:193], v[42:45]
	v_mfma_i32_16x16x64_i8 v[38:41], v[158:161], v[198:201], v[38:41]
	v_mfma_i32_16x16x64_i8 v[34:37], v[166:169], v[198:201], v[34:37]
	s_setprio 0
	s_barrier
	s_mov_b32 m0, s26
	v_lshl_add_u64 v[202:203], s[94:95], 0, v[142:143]
	ds_read_b128 v[170:173], v219 offset:16384
	ds_read_b128 v[174:177], v219 offset:17408
	ds_read_b128 v[178:181], v219 offset:18432
	ds_read_b128 v[182:185], v219 offset:19456
	ds_read_b128 v[186:189], v219 offset:20480
	ds_read_b128 v[190:193], v219 offset:21504
	ds_read_b128 v[194:197], v219 offset:22528
	ds_read_b128 v[198:201], v219 offset:23552
	global_load_lds_dwordx4 v[202:203], off
	v_lshl_add_u64 v[204:205], v[202:203], 0, s[20:21]
	s_mov_b32 m0, s27
	s_nop 0
	global_load_lds_dwordx4 v[204:205], off
	v_lshl_add_u64 v[204:205], v[202:203], 0, s[18:19]
	s_mov_b32 m0, s28
	s_nop 0
	global_load_lds_dwordx4 v[204:205], off
	v_lshl_add_u64 v[204:205], v[202:203], 0, s[92:93]
	s_mov_b32 m0, s29
	s_nop 0
	global_load_lds_dwordx4 v[204:205], off
	v_lshl_add_u64 v[204:205], s[38:39], 0, v[140:141]
	s_mov_b32 m0, s25
	v_lshl_add_u64 v[206:207], v[204:205], 0, s[20:21]
	global_load_lds_dwordx4 v[204:205], off
	s_mov_b32 m0, s58
	s_nop 0
	global_load_lds_dwordx4 v[206:207], off
	s_waitcnt vmcnt(13)
	s_waitcnt lgkmcnt(0)
	s_barrier
; #define G_STAGE_AU(bufoff, gbase) do { G_GLDS((const char*)(gbase) + voffA0, (bufoff) + ldsw); G_GLDS((const char*)(gbase) + vstep64 + voffA0, (bufoff) + ldsw + 8192); } while (0)
; #define X_LDA(b, h) do { if constexpr (MODE == 2) G_LDA8(A8, b, h); else G_LDA(At, b, h); } while (0)
; #define X_LDB0(b, h) do { if constexpr (MODE == 2) G_LDB8(B08, b, h); else G_LDB(B0, b, h); } while (0)
; #define X_LDB1(b, h) do { if constexpr (MODE == 2) G_LDB8(B18, b, h); else G_LDB(B1, b, h); } while (0)
; #define X_MMA0(ai, bj) do { if constexpr (MODE == 2) G_MMA8(ai, bj, A8, B08); else G_MMA(ai, bj, At, B0); } while (0)
; #define X_MMA1(ai, bj) do { if constexpr (MODE == 2) G_MMA8(ai, bj, A8, B18); else G_MMA(ai, bj, At, B1); } while (0)
; #define G_WAIT_V(n) asm volatile("s_waitcnt vmcnt(" #n ")" ::: "memory")
; #define G_WAIT_L(n) asm volatile("s_waitcnt lgkmcnt(" #n ")" ::: "memory")
; #define G_BAR __builtin_amdgcn_s_barrier()
; #define G_SCHED __builtin_amdgcn_sched_barrier(0)
;     ...
;             G_WAIT_V(8); G_WAIT_L(0); G_BAR; X_MMA0(1, 0); X_MMA1(1, 1); G_BAR; G_SCHED;
;             X_LDB0(1, 0); X_LDB1(1, 1); G_SCHED; X_LDA(1, 0); G_STAGE_AU(G_SA(0, 1), a2 + hstep);
;             G_WAIT_V(8); G_WAIT_L(0); G_BAR; X_MMA0(0, 0); X_MMA1(0, 1); G_BAR; G_SCHED;
	s_setprio 1
	s_waitcnt lgkmcnt(0)
	v_mfma_i32_16x16x64_i8 v[96:99], v[132:135], v[170:173], 0
	v_mfma_i32_16x16x64_i8 v[92:95], v[146:149], v[170:173], 0
	v_mfma_i32_16x16x64_i8 v[88:91], v[132:135], v[178:181], 0
	v_mfma_i32_16x16x64_i8 v[84:87], v[146:149], v[178:181], 0
	v_mfma_i32_16x16x64_i8 v[80:83], v[132:135], v[186:189], 0
	v_mfma_i32_16x16x64_i8 v[76:79], v[146:149], v[186:189], 0
	v_mfma_i32_16x16x64_i8 v[72:75], v[132:135], v[194:197], 0
	v_mfma_i32_16x16x64_i8 v[68:71], v[146:149], v[194:197], 0
	v_mfma_i32_16x16x64_i8 v[96:99], v[136:139], v[174:177], v[96:99]
	v_mfma_i32_16x16x64_i8 v[92:95], v[150:153], v[174:177], v[92:95]
	v_mfma_i32_16x16x64_i8 v[88:91], v[136:139], v[182:185], v[88:91]
	v_mfma_i32_16x16x64_i8 v[84:87], v[150:153], v[182:185], v[84:87]
	v_mfma_i32_16x16x64_i8 v[80:83], v[136:139], v[190:193], v[80:83]
	v_mfma_i32_16x16x64_i8 v[76:79], v[150:153], v[190:193], v[76:79]
	v_mfma_i32_16x16x64_i8 v[72:75], v[136:139], v[198:201], v[72:75]
	v_mfma_i32_16x16x64_i8 v[68:71], v[150:153], v[198:201], v[68:71]
	s_setprio 0
	s_setprio 1
	v_mfma_i32_16x16x64_i8 v[30:33], v[154:157], v[170:173], 0
	v_mfma_i32_16x16x64_i8 v[26:29], v[162:165], v[170:173], 0
	v_mfma_i32_16x16x64_i8 v[22:25], v[154:157], v[178:181], 0
	v_mfma_i32_16x16x64_i8 v[18:21], v[162:165], v[178:181], 0
	v_mfma_i32_16x16x64_i8 v[14:17], v[154:157], v[186:189], 0
	v_mfma_i32_16x16x64_i8 v[10:13], v[162:165], v[186:189], 0
	v_mfma_i32_16x16x64_i8 v[6:9], v[154:157], v[194:197], 0
	v_mfma_i32_16x16x64_i8 v[2:5], v[162:165], v[194:197], 0
	v_mfma_i32_16x16x64_i8 v[30:33], v[158:161], v[174:177], v[30:33]
	v_mfma_i32_16x16x64_i8 v[26:29], v[166:169], v[174:177], v[26:29]
	v_mfma_i32_16x16x64_i8 v[22:25], v[158:161], v[182:185], v[22:25]
	v_mfma_i32_16x16x64_i8 v[18:21], v[166:169], v[182:185], v[18:21]
	v_mfma_i32_16x16x64_i8 v[14:17], v[158:161], v[190:193], v[14:17]
	v_mfma_i32_16x16x64_i8 v[10:13], v[166:169], v[190:193], v[10:13]
	v_mfma_i32_16x16x64_i8 v[6:9], v[158:161], v[198:201], v[6:9]
	v_mfma_i32_16x16x64_i8 v[2:5], v[166:169], v[198:201], v[2:5]
	s_setprio 0
	s_barrier
	ds_read_b128 v[132:135], v231
	ds_read_b128 v[136:139], v231 offset:1024
	ds_read_b128 v[146:149], v231 offset:2048
	ds_read_b128 v[150:153], v231 offset:3072
	ds_read_b128 v[154:157], v232
	ds_read_b128 v[158:161], v232 offset:1024
	ds_read_b128 v[162:165], v232 offset:2048
	ds_read_b128 v[166:169], v232 offset:3072
	s_mov_b32 m0, s59
	v_lshl_add_u64 v[206:207], v[204:205], 0, s[18:19]
	ds_read_b128 v[170:173], v219 offset:32768
	ds_read_b128 v[174:177], v219 offset:33792
	ds_read_b128 v[178:181], v219 offset:34816
	ds_read_b128 v[182:185], v219 offset:35840
	ds_read_b128 v[186:189], v219 offset:36864
	ds_read_b128 v[190:193], v219 offset:37888
	ds_read_b128 v[194:197], v219 offset:38912
	ds_read_b128 v[198:201], v219 offset:39936
	global_load_lds_dwordx4 v[206:207], off
	v_lshl_add_u64 v[206:207], v[204:205], 0, s[92:93]
	s_mov_b32 m0, s60
	s_nop 0
	global_load_lds_dwordx4 v[206:207], off
	s_waitcnt vmcnt(8)
	s_waitcnt lgkmcnt(0)
	s_barrier
	s_setprio 1
	s_waitcnt lgkmcnt(0)
	v_mfma_i32_16x16x64_i8 v[128:131], v[132:135], v[170:173], v[128:131]
	v_mfma_i32_16x16x64_i8 v[124:127], v[146:149], v[170:173], v[124:127]
	v_mfma_i32_16x16x64_i8 v[120:123], v[132:135], v[178:181], v[120:123]
	v_mfma_i32_16x16x64_i8 v[116:119], v[146:149], v[178:181], v[116:119]
	v_mfma_i32_16x16x64_i8 v[112:115], v[132:135], v[186:189], v[112:115]
	v_mfma_i32_16x16x64_i8 v[108:111], v[146:149], v[186:189], v[108:111]
	v_mfma_i32_16x16x64_i8 v[104:107], v[132:135], v[194:197], v[104:107]
	v_mfma_i32_16x16x64_i8 v[100:103], v[146:149], v[194:197], v[100:103]
	v_mfma_i32_16x16x64_i8 v[128:131], v[136:139], v[174:177], v[128:131]
	v_mfma_i32_16x16x64_i8 v[124:127], v[150:153], v[174:177], v[124:127]
	v_mfma_i32_16x16x64_i8 v[120:123], v[136:139], v[182:185], v[120:123]
	v_mfma_i32_16x16x64_i8 v[116:119], v[150:153], v[182:185], v[116:119]
	v_mfma_i32_16x16x64_i8 v[112:115], v[136:139], v[190:193], v[112:115]
	v_mfma_i32_16x16x64_i8 v[108:111], v[150:153], v[190:193], v[108:111]
	v_mfma_i32_16x16x64_i8 v[104:107], v[136:139], v[198:201], v[104:107]
	v_mfma_i32_16x16x64_i8 v[100:103], v[150:153], v[198:201], v[100:103]
	s_setprio 0
	s_setprio 1
	v_mfma_i32_16x16x64_i8 v[62:65], v[154:157], v[170:173], v[62:65]
	v_mfma_i32_16x16x64_i8 v[58:61], v[162:165], v[170:173], v[58:61]
	v_mfma_i32_16x16x64_i8 v[54:57], v[154:157], v[178:181], v[54:57]
	v_mfma_i32_16x16x64_i8 v[50:53], v[162:165], v[178:181], v[50:53]
	v_mfma_i32_16x16x64_i8 v[46:49], v[154:157], v[186:189], v[46:49]
	v_mfma_i32_16x16x64_i8 v[42:45], v[162:165], v[186:189], v[42:45]
	v_mfma_i32_16x16x64_i8 v[38:41], v[154:157], v[194:197], v[38:41]
	v_mfma_i32_16x16x64_i8 v[34:37], v[162:165], v[194:197], v[34:37]
	v_mfma_i32_16x16x64_i8 v[62:65], v[158:161], v[174:177], v[62:65]
	v_mfma_i32_16x16x64_i8 v[58:61], v[166:169], v[174:177], v[58:61]
	v_mfma_i32_16x16x64_i8 v[54:57], v[158:161], v[182:185], v[54:57]
	v_mfma_i32_16x16x64_i8 v[50:53], v[166:169], v[182:185], v[50:53]
	v_mfma_i32_16x16x64_i8 v[46:49], v[158:161], v[190:193], v[46:49]
	v_mfma_i32_16x16x64_i8 v[42:45], v[166:169], v[190:193], v[42:45]
	v_mfma_i32_16x16x64_i8 v[38:41], v[158:161], v[198:201], v[38:41]
	v_mfma_i32_16x16x64_i8 v[34:37], v[166:169], v[198:201], v[34:37]
	s_setprio 0
	s_barrier
; #define G_STAGE_B(bufoff, gbase) do { G_GLDS((const char*)(gbase) + voffB0, (bufoff) + ldsw); G_GLDS((const char*)(gbase) + vstep64 + voffB0, (bufoff) + ldsw + 8192); } while (0)
; #define G_STAGE_AU(bufoff, gbase) do { G_GLDS((const char*)(gbase) + voffA0, (bufoff) + ldsw); G_GLDS((const char*)(gbase) + vstep64 + voffA0, (bufoff) + ldsw + 8192); } while (0)
; #define X_LDA(b, h) do { if constexpr (MODE == 2) G_LDA8(A8, b, h); else G_LDA(At, b, h); } while (0)
; #define X_MMA0(ai, bj) do { if constexpr (MODE == 2) G_MMA8(ai, bj, A8, B08); else G_MMA(ai, bj, At, B0); } while (0)
; #define X_MMA1(ai, bj) do { if constexpr (MODE == 2) G_MMA8(ai, bj, A8, B18); else G_MMA(ai, bj, At, B1); } while (0)
; #define G_WAIT_V(n) asm volatile("s_waitcnt vmcnt(" #n ")" ::: "memory")
; #define G_WAIT_L(n) asm volatile("s_waitcnt lgkmcnt(" #n ")" ::: "memory")
; #define G_BAR __builtin_amdgcn_s_barrier()
; #define G_SCHED __builtin_amdgcn_sched_barrier(0)
;     ...
;             X_LDA(1, 1); G_STAGE_B(G_SB(1, 0), b3); G_STAGE_B(G_SB(1, 1), b3 + hstep); G_STAGE_AU(G_SA(1, 0), a3);
;             G_WAIT_V(8); G_WAIT_L(0); G_BAR; X_MMA0(1, 0); X_MMA1(1, 1); G_BAR; G_SCHED;
;         }
	s_mov_b32 m0, s61
	v_lshl_add_u64 v[206:207], v[202:203], 0, s[82:83]
	ds_read_b128 v[170:173], v219 offset:49152
	ds_read_b128 v[174:177], v219 offset:50176
	ds_read_b128 v[178:181], v219 offset:51200
	ds_read_b128 v[182:185], v219 offset:52224
	ds_read_b128 v[186:189], v219 offset:53248
	ds_read_b128 v[190:193], v219 offset:54272
	ds_read_b128 v[194:197], v219 offset:55296
	ds_read_b128 v[198:201], v219 offset:56320
	global_load_lds_dwordx4 v[206:207], off
	v_lshl_add_u64 v[206:207], v[202:203], 0, s[22:23]
	s_mov_b32 m0, s62
	s_nop 0
	global_load_lds_dwordx4 v[206:207], off
	v_lshl_add_u64 v[206:207], v[202:203], 0, s[88:89]
	s_mov_b32 m0, s65
	v_lshl_add_u64 v[202:203], v[202:203], 0, s[74:75]
	global_load_lds_dwordx4 v[206:207], off
	s_mov_b32 m0, s66
	s_nop 0
	global_load_lds_dwordx4 v[202:203], off
	v_lshl_add_u64 v[202:203], v[204:205], 0, s[82:83]
	s_mov_b32 m0, s63
	s_nop 0
	global_load_lds_dwordx4 v[202:203], off
	v_lshl_add_u64 v[202:203], v[204:205], 0, s[22:23]
	s_mov_b32 m0, s64
	s_nop 0
	global_load_lds_dwordx4 v[202:203], off
	s_waitcnt vmcnt(8)
	s_waitcnt lgkmcnt(0)
	s_barrier
	s_setprio 1
	s_waitcnt lgkmcnt(0)
	v_mfma_i32_16x16x64_i8 v[96:99], v[132:135], v[170:173], v[96:99]
	v_mfma_i32_16x16x64_i8 v[92:95], v[146:149], v[170:173], v[92:95]
	v_mfma_i32_16x16x64_i8 v[88:91], v[132:135], v[178:181], v[88:91]
	v_mfma_i32_16x16x64_i8 v[84:87], v[146:149], v[178:181], v[84:87]
	v_mfma_i32_16x16x64_i8 v[80:83], v[132:135], v[186:189], v[80:83]
	v_mfma_i32_16x16x64_i8 v[76:79], v[146:149], v[186:189], v[76:79]
	v_mfma_i32_16x16x64_i8 v[72:75], v[132:135], v[194:197], v[72:75]
	v_mfma_i32_16x16x64_i8 v[68:71], v[146:149], v[194:197], v[68:71]
	v_mfma_i32_16x16x64_i8 v[96:99], v[136:139], v[174:177], v[96:99]
	v_mfma_i32_16x16x64_i8 v[92:95], v[150:153], v[174:177], v[92:95]
	v_mfma_i32_16x16x64_i8 v[88:91], v[136:139], v[182:185], v[88:91]
	v_mfma_i32_16x16x64_i8 v[84:87], v[150:153], v[182:185], v[84:87]
	v_mfma_i32_16x16x64_i8 v[80:83], v[136:139], v[190:193], v[80:83]
	v_mfma_i32_16x16x64_i8 v[76:79], v[150:153], v[190:193], v[76:79]
	v_mfma_i32_16x16x64_i8 v[72:75], v[136:139], v[198:201], v[72:75]
	v_mfma_i32_16x16x64_i8 v[68:71], v[150:153], v[198:201], v[68:71]
	s_setprio 0
	s_setprio 1
	v_mfma_i32_16x16x64_i8 v[30:33], v[154:157], v[170:173], v[30:33]
	v_mfma_i32_16x16x64_i8 v[26:29], v[162:165], v[170:173], v[26:29]
	v_mfma_i32_16x16x64_i8 v[22:25], v[154:157], v[178:181], v[22:25]
	v_mfma_i32_16x16x64_i8 v[18:21], v[162:165], v[178:181], v[18:21]
	v_mfma_i32_16x16x64_i8 v[14:17], v[154:157], v[186:189], v[14:17]
	v_mfma_i32_16x16x64_i8 v[10:13], v[162:165], v[186:189], v[10:13]
	v_mfma_i32_16x16x64_i8 v[6:9], v[154:157], v[194:197], v[6:9]
	v_mfma_i32_16x16x64_i8 v[2:5], v[162:165], v[194:197], v[2:5]
	v_mfma_i32_16x16x64_i8 v[30:33], v[158:161], v[174:177], v[30:33]
	v_mfma_i32_16x16x64_i8 v[26:29], v[166:169], v[174:177], v[26:29]
	v_mfma_i32_16x16x64_i8 v[22:25], v[158:161], v[182:185], v[22:25]
	v_mfma_i32_16x16x64_i8 v[18:21], v[166:169], v[182:185], v[18:21]
	v_mfma_i32_16x16x64_i8 v[14:17], v[158:161], v[190:193], v[14:17]
	v_mfma_i32_16x16x64_i8 v[10:13], v[166:169], v[190:193], v[10:13]
	v_mfma_i32_16x16x64_i8 v[6:9], v[158:161], v[198:201], v[6:9]
	v_mfma_i32_16x16x64_i8 v[2:5], v[166:169], v[198:201], v[2:5]
	s_setprio 0
	s_barrier
	s_add_i32 s11, s11, 2
	s_add_u32 s0, s0, 0x100
	s_addc_u32 s1, s1, 0
	s_add_u32 s8, s8, 0x100
	s_addc_u32 s9, s9, 0
	s_cmp_gt_u32 s11, 5
	s_cbranch_scc1 .Lmy_peel_inproj_exit

;     template <int KIND>
;     __device__ __forceinline__ void run(const f32x4 (&acc)[2][2][4][2], const Unit& u, int wr, int wc, int fr, int fq) const {
;         const int row0 = u.pm * BM + wr * 64 + fr, col0 = u.pn * BM + wc * 32 + 8 * fq;
;         const float sa_lo = sa[u.pm * BM + wr * 64 + fr + 16 * fq], sa_hi = sa[u.pm * BM + HALF + wr * 64 + fr + 16 * fq];
; #pragma unroll
;         for (int bj = 0; bj < 2; ++bj) {
;             f32x2_t sc2[4], aux2[4];
; #pragma unroll
;             for (int j = 0; j < 4; ++j) {
;                 const float k0 = (KIND == 4) ? (0.125f * LOG2E / 127.0f) : (1.0f / 127.0f);
;                 sc2[j] = (f32x2_t){wmax[col0 + bj * HALF + 2 * j] * k0, wmax[col0 + bj * HALF + 2 * j + 1] * k0};
;                 if (KIND == 1) aux2[j] = (f32x2_t){lb[col0 - C_HG + bj * HALF + 2 * j], lb[col0 - C_HG + bj * HALF + 2 * j + 1]};
;                 else if (KIND == 3) aux2[j] = (f32x2_t){gain[col0 - C_HGATE + bj * HALF + 2 * j], gain[col0 - C_HGATE + bj * HALF + 2 * j + 1]};
;                 else aux2[j] = (f32x2_t){0.f, 0.f};
;             }
; #pragma unroll
;             for (int ai = 0; ai < 2; ++ai)
; #pragma unroll
;                 for (int m = 0; m < 4; ++m) { const int row = row0 + ai * HALF + m * 16; const float a = __shfl(ai ? sa_hi : sa_lo, 16 * m + fr);
;                     const f32x4 f0 = __builtin_convertvector(__builtin_bit_cast(i32x4, acc[ai][bj][m][0]), f32x4), f1 = __builtin_convertvector(__builtin_bit_cast(i32x4, acc[ai][bj][m][1]), f32x4);
;                     f32x2_t v[4] = {(f32x2_t){f0[0], f0[1]}, (f32x2_t){f0[2], f0[3]}, (f32x2_t){f1[0], f1[1]}, (f32x2_t){f1[2], f1[3]}};
; #pragma unroll
;                     for (int j = 0; j < 4; ++j) {
;                         v[j] = v[j] * (sc2[j] * (f32x2_t){a, a});
;                         if (KIND == 0 || KIND == 1 || KIND == 3) {
;                             const f32x2_t e = v[j] * (f32x2_t){-LOG2E, -LOG2E};
;                             const f32x2_t dn = (f32x2_t){__builtin_amdgcn_exp2f(e[0]), __builtin_amdgcn_exp2f(e[1])} + (f32x2_t){1.0f, 1.0f};
;                             const f32x2_t sg = (f32x2_t){fast_rcp(dn[0]), fast_rcp(dn[1])};
;                             if (KIND == 0) v[j] = v[j] * sg;
;                             else if (KIND == 3) v[j] = (v[j] * sg) * aux2[j];
.LBB0_206:
	s_mov_b64 s[0:1], -1
	s_cmp_gt_u32 s2, 1
	v_lshl_or_b32 v146, s2, 8, v216
	s_cbranch_scc0 .LBB0_212
	s_lshl_b32 s0, s90, 8
	v_add_u32_e32 v175, s0, v212
	v_or_b32_e32 v132, v175, v214
	v_ashrrev_i32_e32 v133, 31, v132
	v_add_u32_e32 v134, s0, v215
	v_ashrrev_i32_e32 v147, 31, v146
	v_lshl_add_u64 v[132:133], v[132:133], 2, s[46:47]
	v_ashrrev_i32_e32 v135, 31, v134
	v_lshl_add_u64 v[148:149], v[146:147], 2, s[48:49]
	v_lshl_add_u64 v[134:135], v[134:135], 2, s[46:47]
	v_mov_b32_e32 v154, v236
	v_mov_b32_e32 v155, v237
	s_ashr_i32 s16, s2, 1
	s_mov_b64 s[10:11], -1
	s_mov_b64 s[0:1], 0
	s_cmp_lt_i32 s16, 3
	s_mov_b64 s[8:9], 0
	s_cbranch_scc1 .LBB0_220
	s_cmp_gt_i32 s16, 3
	s_cbranch_scc0 .LBB0_217
	s_cmp_eq_u32 s16, 4
	s_mov_b64 s[8:9], -1
	s_cbranch_scc0 .LBB0_211
	v_mov_b32_e32 v150, v242
	v_mov_b32_e32 v151, v243
	v_mov_b32_e32 v134, v238
	v_mov_b32_e32 v135, v239
	v_mov_b32_e32 v136, v240
	v_mov_b32_e32 v137, v241
	global_load_dwordx4 v[236:239], v[148:149], off offset:528
	global_load_dwordx4 v[240:243], v[148:149], off offset:512
	s_mov_b32 s6, 0x3aba1e78
	v_cvt_f32_i32_e32 v157, v129
	v_cvt_f32_i32_e32 v156, v128
	v_cvt_f32_i32_e32 v153, v131
	v_cvt_f32_i32_e32 v152, v130
	v_pk_mul_f32 v[132:133], v[154:155], s[6:7] op_sel_hi:[1,0]
	v_cvt_f32_i32_e32 v161, v125
	v_cvt_f32_i32_e32 v160, v124
	v_cvt_f32_i32_e32 v159, v127
	v_cvt_f32_i32_e32 v158, v126
	v_lshlrev_b64 v[164:165], 1, v[146:147]
	v_cvt_f32_i32_e32 v169, v117
	v_cvt_f32_i32_e32 v168, v116
	v_cvt_f32_i32_e32 v167, v119
	v_cvt_f32_i32_e32 v166, v118
	v_cvt_f32_i32_e32 v173, v109
	v_cvt_f32_i32_e32 v172, v108
	v_cvt_f32_i32_e32 v179, v101
	v_cvt_f32_i32_e32 v178, v100
	v_cvt_f32_i32_e32 v183, v93
	v_cvt_f32_i32_e32 v182, v92
	v_cvt_f32_i32_e32 v187, v85
	v_cvt_f32_i32_e32 v186, v84
	s_mov_b64 s[8:9], 0
	v_pk_mul_f32 v[138:139], v[134:135], s[6:7] op_sel_hi:[1,0]
	v_pk_mul_f32 v[134:135], v[150:151], s[6:7] op_sel_hi:[1,0]
	v_lshlrev_b32_e32 v150, 2, v233
	ds_bpermute_b32 v66, v150, v209
	v_pk_mul_f32 v[136:137], v[136:137], s[6:7] op_sel_hi:[1,0]
	v_or_b32_e32 v151, 16, v175
	ds_bpermute_b32 v174, v150, v208 offset:128
	s_waitcnt lgkmcnt(1)
	v_pk_mul_f32 v[162:163], v[132:133], v[66:67] op_sel_hi:[1,0]
	s_nop 0
	v_pk_mul_f32 v[156:157], v[156:157], v[162:163]
	v_pk_mul_f32 v[162:163], v[138:139], v[66:67] op_sel_hi:[1,0]
	s_waitcnt lgkmcnt(0)
	v_pk_mul_f32 v[190:191], v[132:133], v[174:175] op_sel_hi:[1,0]
	v_pk_mul_f32 v[152:153], v[152:153], v[162:163]
	v_pk_mul_f32 v[162:163], v[136:137], v[66:67] op_sel_hi:[1,0]
	s_nop 0
	v_pk_mul_f32 v[160:161], v[160:161], v[162:163]
	v_pk_mul_f32 v[162:163], v[134:135], v[66:67] op_sel_hi:[1,0]
	v_cvt_pk_bf16_f32 v160, v160, v161
	v_pk_mul_f32 v[162:163], v[158:159], v[162:163]
	v_cvt_pk_bf16_f32 v159, v152, v153
	v_cvt_pk_bf16_f32 v161, v162, v163
	v_mov_b64_e32 v[162:163], s[14:15]
	v_mad_i64_i32 v[152:153], s[2:3], v175, s81, v[162:163]
	v_cvt_pk_bf16_f32 v158, v156, v157
	v_lshl_add_u64 v[156:157], v[152:153], 0, v[164:165]
	ds_bpermute_b32 v152, v150, v209 offset:64
	global_store_dwordx4 v[156:157], v[158:161], off
	s_waitcnt lgkmcnt(0)
	v_pk_mul_f32 v[170:171], v[132:133], v[152:153] op_sel_hi:[1,0]
	v_cvt_f32_i32_e32 v161, v121
	v_cvt_f32_i32_e32 v160, v120
	v_cvt_f32_i32_e32 v159, v123
	v_cvt_f32_i32_e32 v158, v122
	v_pk_mul_f32 v[160:161], v[160:161], v[170:171]
	v_pk_mul_f32 v[170:171], v[138:139], v[152:153] op_sel_hi:[1,0]
	s_nop 0
	v_pk_mul_f32 v[158:159], v[158:159], v[170:171]
	v_pk_mul_f32 v[170:171], v[136:137], v[152:153] op_sel_hi:[1,0]
	s_nop 0
	v_pk_mul_f32 v[168:169], v[168:169], v[170:171]
	v_pk_mul_f32 v[170:171], v[134:135], v[152:153] op_sel_hi:[1,0]
	v_cvt_pk_bf16_f32 v168, v168, v169
	v_pk_mul_f32 v[170:171], v[166:167], v[170:171]
	v_cvt_pk_bf16_f32 v167, v158, v159
	v_mad_i64_i32 v[158:159], s[2:3], v151, s81, v[162:163]
	v_cvt_pk_bf16_f32 v166, v160, v161
	v_lshl_add_u64 v[160:161], v[158:159], 0, v[164:165]
	ds_bpermute_b32 v158, v150, v209 offset:128
	v_cvt_pk_bf16_f32 v169, v170, v171
	global_store_dwordx4 v[160:161], v[166:169], off
	v_cvt_f32_i32_e32 v171, v111
	v_cvt_f32_i32_e32 v170, v110
	v_cvt_f32_i32_e32 v169, v113
	v_cvt_f32_i32_e32 v168, v112
	v_cvt_f32_i32_e32 v167, v115
	v_cvt_f32_i32_e32 v166, v114
	s_waitcnt lgkmcnt(0)
	v_pk_mul_f32 v[176:177], v[132:133], v[158:159] op_sel_hi:[1,0]
	v_or_b32_e32 v151, 32, v175
	v_pk_mul_f32 v[168:169], v[168:169], v[176:177]
	v_pk_mul_f32 v[176:177], v[138:139], v[158:159] op_sel_hi:[1,0]
	v_cvt_pk_bf16_f32 v168, v168, v169
	v_pk_mul_f32 v[166:167], v[166:167], v[176:177]
	v_pk_mul_f32 v[176:177], v[136:137], v[158:159] op_sel_hi:[1,0]
	v_cvt_pk_bf16_f32 v169, v166, v167
	v_pk_mul_f32 v[172:173], v[172:173], v[176:177]
	v_pk_mul_f32 v[176:177], v[134:135], v[158:159] op_sel_hi:[1,0]
	v_mad_i64_i32 v[166:167], s[2:3], v151, s81, v[162:163]
	v_pk_mul_f32 v[176:177], v[170:171], v[176:177]
	v_cvt_pk_bf16_f32 v170, v172, v173
	v_cvt_pk_bf16_f32 v171, v176, v177
	v_lshl_add_u64 v[166:167], v[166:167], 0, v[164:165]
	global_store_dwordx4 v[166:167], v[168:171], off
	ds_bpermute_b32 v168, v150, v209 offset:192
	v_cvt_f32_i32_e32 v173, v105
	v_cvt_f32_i32_e32 v172, v104
	v_cvt_f32_i32_e32 v171, v107
	v_cvt_f32_i32_e32 v170, v106
	v_cvt_f32_i32_e32 v177, v103
	v_cvt_f32_i32_e32 v176, v102
	s_waitcnt lgkmcnt(0)
; __device__ __forceinline__ unsigned cvt_pk_bf16(float lo, float hi) { f32x2_t v = {lo, hi}; bf16x2_t b = __builtin_convertvector(v, bf16x2_t); return __builtin_bit_cast(unsigned, b); }
; __device__ __forceinline__ float fast_rcp(float x) { return __builtin_amdgcn_rcpf(x); }
;     template <int KIND>
;     __device__ __forceinline__ void run(const f32x4 (&acc)[2][2][4][2], const Unit& u, int wr, int wc, int fr, int fq) const {
;     ...
;             for (int ai = 0; ai < 2; ++ai)
; #pragma unroll
;                 for (int m = 0; m < 4; ++m) { const int row = row0 + ai * HALF + m * 16; const float a = __shfl(ai ? sa_hi : sa_lo, 16 * m + fr);
;                     const f32x4 f0 = __builtin_convertvector(__builtin_bit_cast(i32x4, acc[ai][bj][m][0]), f32x4), f1 = __builtin_convertvector(__builtin_bit_cast(i32x4, acc[ai][bj][m][1]), f32x4);
;                     f32x2_t v[4] = {(f32x2_t){f0[0], f0[1]}, (f32x2_t){f0[2], f0[3]}, (f32x2_t){f1[0], f1[1]}, (f32x2_t){f1[2], f1[3]}};
; #pragma unroll
;                     for (int j = 0; j < 4; ++j) {
;                         v[j] = v[j] * (sc2[j] * (f32x2_t){a, a});
;                         if (KIND == 0 || KIND == 1 || KIND == 3) {
;                             const f32x2_t e = v[j] * (f32x2_t){-LOG2E, -LOG2E};
;                             const f32x2_t dn = (f32x2_t){__builtin_amdgcn_exp2f(e[0]), __builtin_amdgcn_exp2f(e[1])} + (f32x2_t){1.0f, 1.0f};
;                             const f32x2_t sg = (f32x2_t){fast_rcp(dn[0]), fast_rcp(dn[1])};
;                             if (KIND == 0) v[j] = v[j] * sg;
;                             else if (KIND == 3) v[j] = (v[j] * sg) * aux2[j];
;                             else { const f32x2_t f = __builtin_elementwise_fma((f32x2_t){1.0f, 1.0f} - aux2[j], sg, aux2[j]);
;                                 v[j] = (f32x2_t){fmaxf(__logf(f[0]), -60.0f), fmaxf(__logf(f[1]), -60.0f)}; }
;                         }
;                     }
;                     u32x4 w; w.x = cvt_pk_bf16(v[0][0], v[0][1]); w.y = cvt_pk_bf16(v[1][0], v[1][1]); w.z = cvt_pk_bf16(v[2][0], v[2][1]); w.w = cvt_pk_bf16(v[3][0], v[3][1]);
;                     *(u32x4*)(O + (size_t)row * NPROJ + col0 + bj * HALF) = w; }
	v_pk_mul_f32 v[180:181], v[132:133], v[168:169] op_sel_hi:[1,0]
	v_or_b32_e32 v151, 48, v175
	v_pk_mul_f32 v[172:173], v[172:173], v[180:181]
	v_pk_mul_f32 v[180:181], v[138:139], v[168:169] op_sel_hi:[1,0]
	v_add_u32_e32 v153, 0xb0, v175
	v_pk_mul_f32 v[180:181], v[170:171], v[180:181]
	v_pk_mul_f32 v[170:171], v[136:137], v[168:169] op_sel_hi:[1,0]
	s_nop 0
	v_pk_mul_f32 v[178:179], v[178:179], v[170:171]
	v_pk_mul_f32 v[170:171], v[134:135], v[168:169] op_sel_hi:[1,0]
	s_nop 0
	v_pk_mul_f32 v[176:177], v[176:177], v[170:171]
	v_cvt_pk_bf16_f32 v170, v172, v173
	v_cvt_pk_bf16_f32 v173, v176, v177
	v_mad_i64_i32 v[176:177], s[2:3], v151, s81, v[162:163]
	v_cvt_pk_bf16_f32 v171, v180, v181
	v_cvt_pk_bf16_f32 v172, v178, v179
	v_lshl_add_u64 v[178:179], v[176:177], 0, v[164:165]
	global_store_dwordx4 v[178:179], v[170:173], off
	ds_bpermute_b32 v170, v150, v208
	v_cvt_f32_i32_e32 v177, v97
	v_cvt_f32_i32_e32 v176, v96
	v_cvt_f32_i32_e32 v173, v99
	v_cvt_f32_i32_e32 v172, v98
	v_cvt_f32_i32_e32 v181, v95
	v_cvt_f32_i32_e32 v180, v94
	s_waitcnt lgkmcnt(0)
	v_pk_mul_f32 v[184:185], v[132:133], v[170:171] op_sel_hi:[1,0]
	v_add_u32_e32 v151, 0x80, v175
	v_pk_mul_f32 v[176:177], v[176:177], v[184:185]
	v_pk_mul_f32 v[184:185], v[138:139], v[170:171] op_sel_hi:[1,0]
	s_nop 0
	v_pk_mul_f32 v[172:173], v[172:173], v[184:185]
	v_pk_mul_f32 v[184:185], v[136:137], v[170:171] op_sel_hi:[1,0]
	s_nop 0
	v_pk_mul_f32 v[184:185], v[182:183], v[184:185]
	v_pk_mul_f32 v[182:183], v[134:135], v[170:171] op_sel_hi:[1,0]
	v_cvt_pk_bf16_f32 v184, v184, v185
	v_pk_mul_f32 v[180:181], v[180:181], v[182:183]
	v_cvt_pk_bf16_f32 v183, v172, v173
	v_mad_i64_i32 v[172:173], s[2:3], v151, s81, v[162:163]
	v_cvt_pk_bf16_f32 v185, v180, v181
	v_lshl_add_u64 v[180:181], v[172:173], 0, v[164:165]
	ds_bpermute_b32 v172, v150, v208 offset:64
	v_cvt_pk_bf16_f32 v182, v176, v177
	global_store_dwordx4 v[180:181], v[182:185], off
	v_cvt_f32_i32_e32 v177, v91
	v_cvt_f32_i32_e32 v176, v90
	v_cvt_f32_i32_e32 v183, v89
	v_cvt_f32_i32_e32 v182, v88
	v_cvt_f32_i32_e32 v185, v87
	v_cvt_f32_i32_e32 v184, v86
	s_waitcnt lgkmcnt(0)
	v_pk_mul_f32 v[188:189], v[132:133], v[172:173] op_sel_hi:[1,0]
	v_add_u32_e32 v151, 0x90, v175
	v_pk_mul_f32 v[182:183], v[182:183], v[188:189]
	v_pk_mul_f32 v[188:189], v[138:139], v[172:173] op_sel_hi:[1,0]
	s_nop 0
	v_pk_mul_f32 v[176:177], v[176:177], v[188:189]
	v_pk_mul_f32 v[188:189], v[136:137], v[172:173] op_sel_hi:[1,0]
	s_nop 0
	v_pk_mul_f32 v[186:187], v[186:187], v[188:189]
	v_pk_mul_f32 v[188:189], v[134:135], v[172:173] op_sel_hi:[1,0]
	v_cvt_pk_bf16_f32 v186, v186, v187
	v_pk_mul_f32 v[188:189], v[184:185], v[188:189]
	v_cvt_pk_bf16_f32 v185, v176, v177
	v_mad_i64_i32 v[176:177], s[2:3], v151, s81, v[162:163]
	v_cvt_pk_bf16_f32 v184, v182, v183
	v_cvt_pk_bf16_f32 v187, v188, v189
	v_lshl_add_u64 v[182:183], v[176:177], 0, v[164:165]
	global_store_dwordx4 v[182:183], v[184:187], off
	v_cvt_f32_i32_e32 v177, v83
	v_cvt_f32_i32_e32 v176, v82
	v_cvt_f32_i32_e32 v185, v81
	v_cvt_f32_i32_e32 v184, v80
	v_cvt_f32_i32_e32 v189, v77
	v_cvt_f32_i32_e32 v188, v76
	v_cvt_f32_i32_e32 v187, v79
	v_cvt_f32_i32_e32 v186, v78
	v_pk_mul_f32 v[184:185], v[184:185], v[190:191]
	v_pk_mul_f32 v[190:191], v[138:139], v[174:175] op_sel_hi:[1,0]
	v_add_u32_e32 v151, 0xa0, v175
	v_pk_mul_f32 v[176:177], v[176:177], v[190:191]
	v_pk_mul_f32 v[190:191], v[136:137], v[174:175] op_sel_hi:[1,0]
	s_nop 0
	v_pk_mul_f32 v[188:189], v[188:189], v[190:191]
	v_pk_mul_f32 v[190:191], v[134:135], v[174:175] op_sel_hi:[1,0]
	v_cvt_pk_bf16_f32 v188, v188, v189
	v_pk_mul_f32 v[190:191], v[186:187], v[190:191]
	v_cvt_pk_bf16_f32 v187, v176, v177
	v_mad_i64_i32 v[176:177], s[2:3], v151, s81, v[162:163]
	v_cvt_pk_bf16_f32 v186, v184, v185
	v_lshl_add_u64 v[184:185], v[176:177], 0, v[164:165]
	ds_bpermute_b32 v176, v150, v208 offset:192
	v_cvt_pk_bf16_f32 v189, v190, v191
	v_cvt_f32_i32_e32 v191, v69
	v_cvt_f32_i32_e32 v190, v68
	global_store_dwordx4 v[184:185], v[186:189], off
	v_cvt_f32_i32_e32 v151, v75
	v_cvt_f32_i32_e32 v150, v74
	v_cvt_f32_i32_e32 v187, v73
	v_cvt_f32_i32_e32 v186, v72
	v_cvt_f32_i32_e32 v189, v71
	v_cvt_f32_i32_e32 v188, v70
	s_waitcnt lgkmcnt(0)
	v_pk_mul_f32 v[136:137], v[136:137], v[176:177] op_sel_hi:[1,0]
	v_pk_mul_f32 v[132:133], v[132:133], v[176:177] op_sel_hi:[1,0]
	v_pk_mul_f32 v[138:139], v[138:139], v[176:177] op_sel_hi:[1,0]
	v_pk_mul_f32 v[136:137], v[190:191], v[136:137]
	v_pk_mul_f32 v[134:135], v[134:135], v[176:177] op_sel_hi:[1,0]
	v_pk_mul_f32 v[132:133], v[186:187], v[132:133]
	v_pk_mul_f32 v[138:139], v[150:151], v[138:139]
	v_pk_mul_f32 v[150:151], v[188:189], v[134:135]
	v_cvt_pk_bf16_f32 v134, v136, v137
	v_mad_i64_i32 v[136:137], s[2:3], v153, s81, v[162:163]
	v_cvt_pk_bf16_f32 v132, v132, v133
	v_cvt_pk_bf16_f32 v133, v138, v139
	v_cvt_pk_bf16_f32 v135, v150, v151
	v_lshl_add_u64 v[136:137], v[136:137], 0, v[164:165]
	global_store_dwordx4 v[136:137], v[132:135], off
	s_nop 1
	s_waitcnt vmcnt(8)
;     template <int KIND>
;     __device__ __forceinline__ void run(const f32x4 (&acc)[2][2][4][2], const Unit& u, int wr, int wc, int fr, int fq) const {
;     ...
;         for (int bj = 0; bj < 2; ++bj) {
;             f32x2_t sc2[4], aux2[4];
; #pragma unroll
;             for (int j = 0; j < 4; ++j) {
;                 const float k0 = (KIND == 4) ? (0.125f * LOG2E / 127.0f) : (1.0f / 127.0f);
;                 sc2[j] = (f32x2_t){wmax[col0 + bj * HALF + 2 * j] * k0, wmax[col0 + bj * HALF + 2 * j + 1] * k0};
;                 if (KIND == 1) aux2[j] = (f32x2_t){lb[col0 - C_HG + bj * HALF + 2 * j], lb[col0 - C_HG + bj * HALF + 2 * j + 1]};
;                 else if (KIND == 3) aux2[j] = (f32x2_t){gain[col0 - C_HGATE + bj * HALF + 2 * j], gain[col0 - C_HGATE + bj * HALF + 2 * j + 1]};
;                 else aux2[j] = (f32x2_t){0.f, 0.f};
;             }
; #pragma unroll
;             for (int ai = 0; ai < 2; ++ai)
; #pragma unroll
;                 for (int m = 0; m < 4; ++m) { const int row = row0 + ai * HALF + m * 16; const float a = __shfl(ai ? sa_hi : sa_lo, 16 * m + fr);
;                     const f32x4 f0 = __builtin_convertvector(__builtin_bit_cast(i32x4, acc[ai][bj][m][0]), f32x4), f1 = __builtin_convertvector(__builtin_bit_cast(i32x4, acc[ai][bj][m][1]), f32x4);
;                     f32x2_t v[4] = {(f32x2_t){f0[0], f0[1]}, (f32x2_t){f0[2], f0[3]}, (f32x2_t){f1[0], f1[1]}, (f32x2_t){f1[2], f1[3]}};
; #pragma unroll
;                     for (int j = 0; j < 4; ++j) {
;                         v[j] = v[j] * (sc2[j] * (f32x2_t){a, a});
;                         if (KIND == 0 || KIND == 1 || KIND == 3) {
;                             const f32x2_t e = v[j] * (f32x2_t){-LOG2E, -LOG2E};
;                             const f32x2_t dn = (f32x2_t){__builtin_amdgcn_exp2f(e[0]), __builtin_amdgcn_exp2f(e[1])} + (f32x2_t){1.0f, 1.0f};
;                             const f32x2_t sg = (f32x2_t){fast_rcp(dn[0]), fast_rcp(dn[1])};
;                             if (KIND == 0) v[j] = v[j] * sg;
;                             else if (KIND == 3) v[j] = (v[j] * sg) * aux2[j];
;                             else { const f32x2_t f = __builtin_elementwise_fma((f32x2_t){1.0f, 1.0f} - aux2[j], sg, aux2[j]);
;                                 v[j] = (f32x2_t){fmaxf(__logf(f[0]), -60.0f), fmaxf(__logf(f[1]), -60.0f)}; }
;                         }
;                     }
	v_mov_b32_e32 v132, v236
	v_mov_b32_e32 v133, v237
	v_mov_b32_e32 v134, v238
	v_mov_b32_e32 v135, v239
	v_mov_b32_e32 v136, v240
	v_mov_b32_e32 v137, v241
	v_mov_b32_e32 v138, v242
	v_mov_b32_e32 v139, v243
	v_cvt_f32_i32_e32 v189, v59
	v_cvt_f32_i32_e32 v188, v58
	v_cvt_f32_i32_e32 v187, v61
	v_cvt_f32_i32_e32 v186, v60
	v_mad_i64_i32 v[150:151], s[2:3], v153, s81, 0
	v_pk_mul_f32 v[132:133], v[132:133], s[6:7] op_sel_hi:[1,0]
	v_pk_mul_f32 v[164:165], v[138:139], s[6:7] op_sel_hi:[1,0]
	v_cvt_f32_i32_e32 v139, v63
	v_cvt_f32_i32_e32 v138, v62
	v_pk_mul_f32 v[162:163], v[136:137], s[6:7] op_sel_hi:[1,0]
	v_cvt_f32_i32_e32 v137, v65
	v_cvt_f32_i32_e32 v136, v64
	v_pk_mul_f32 v[190:191], v[66:67], v[162:163] op_sel_hi:[0,1]
	v_pk_mul_f32 v[138:139], v[138:139], v[190:191]
	v_pk_mul_f32 v[190:191], v[66:67], v[164:165] op_sel_hi:[0,1]
	v_pk_mul_f32 v[134:135], v[134:135], s[6:7] op_sel_hi:[1,0]
	v_pk_mul_f32 v[190:191], v[136:137], v[190:191]
	v_pk_mul_f32 v[136:137], v[66:67], v[132:133] op_sel_hi:[0,1]
	v_pk_mul_f32 v[188:189], v[188:189], v[136:137]
	v_pk_mul_f32 v[136:137], v[66:67], v[134:135] op_sel_hi:[0,1]
	v_pk_mul_f32 v[186:187], v[186:187], v[136:137]
	v_cvt_pk_bf16_f32 v136, v138, v139
	v_cvt_pk_bf16_f32 v137, v190, v191
	v_cvt_pk_bf16_f32 v138, v188, v189
	v_cvt_pk_bf16_f32 v139, v186, v187
	global_store_dwordx4 v[156:157], v[136:139], off offset:256
	v_cvt_f32_i32_e32 v187, v51
	v_cvt_f32_i32_e32 v186, v50
	v_cvt_f32_i32_e32 v139, v55
	v_cvt_f32_i32_e32 v138, v54
	v_cvt_f32_i32_e32 v137, v57
	v_cvt_f32_i32_e32 v136, v56
	v_cvt_f32_i32_e32 v157, v53
	v_cvt_f32_i32_e32 v156, v52
	v_pk_mul_f32 v[188:189], v[152:153], v[162:163] op_sel_hi:[0,1]
	v_pk_mul_f32 v[138:139], v[138:139], v[188:189]
	v_pk_mul_f32 v[188:189], v[152:153], v[164:165] op_sel_hi:[0,1]
	v_pk_mul_f32 v[188:189], v[136:137], v[188:189]
	v_pk_mul_f32 v[136:137], v[152:153], v[132:133] op_sel_hi:[0,1]
	v_pk_mul_f32 v[186:187], v[186:187], v[136:137]
	v_pk_mul_f32 v[136:137], v[152:153], v[134:135] op_sel_hi:[0,1]
	v_pk_mul_f32 v[152:153], v[156:157], v[136:137]
	v_cvt_pk_bf16_f32 v136, v138, v139
	v_cvt_pk_bf16_f32 v137, v188, v189
	v_cvt_pk_bf16_f32 v138, v186, v187
	v_cvt_pk_bf16_f32 v139, v152, v153
	global_store_dwordx4 v[160:161], v[136:139], off offset:256
	v_cvt_f32_i32_e32 v157, v43
	v_cvt_f32_i32_e32 v156, v42
	v_cvt_f32_i32_e32 v139, v47
	v_cvt_f32_i32_e32 v138, v46
	v_cvt_f32_i32_e32 v137, v49
	v_cvt_f32_i32_e32 v136, v48
	v_cvt_f32_i32_e32 v153, v45
	v_cvt_f32_i32_e32 v152, v44
	v_pk_mul_f32 v[160:161], v[158:159], v[162:163] op_sel_hi:[0,1]
	v_pk_mul_f32 v[138:139], v[138:139], v[160:161]
	v_pk_mul_f32 v[160:161], v[158:159], v[164:165] op_sel_hi:[0,1]
	v_pk_mul_f32 v[160:161], v[136:137], v[160:161]
	v_pk_mul_f32 v[136:137], v[158:159], v[132:133] op_sel_hi:[0,1]
	v_pk_mul_f32 v[156:157], v[156:157], v[136:137]
	v_pk_mul_f32 v[136:137], v[158:159], v[134:135] op_sel_hi:[0,1]
	v_pk_mul_f32 v[152:153], v[152:153], v[136:137]
	v_cvt_pk_bf16_f32 v136, v138, v139
	v_cvt_pk_bf16_f32 v137, v160, v161
	v_cvt_pk_bf16_f32 v138, v156, v157
	v_cvt_pk_bf16_f32 v139, v152, v153
	global_store_dwordx4 v[166:167], v[136:139], off offset:256
	v_cvt_f32_i32_e32 v157, v35
	v_cvt_f32_i32_e32 v156, v34
	v_cvt_f32_i32_e32 v139, v39
	v_cvt_f32_i32_e32 v138, v38
	v_cvt_f32_i32_e32 v137, v41
	v_cvt_f32_i32_e32 v136, v40
	v_cvt_f32_i32_e32 v153, v37
	v_cvt_f32_i32_e32 v152, v36
	v_pk_mul_f32 v[158:159], v[168:169], v[162:163] op_sel_hi:[0,1]
	v_pk_mul_f32 v[138:139], v[138:139], v[158:159]
	v_pk_mul_f32 v[158:159], v[168:169], v[164:165] op_sel_hi:[0,1]
	v_pk_mul_f32 v[158:159], v[136:137], v[158:159]
	v_pk_mul_f32 v[136:137], v[168:169], v[132:133] op_sel_hi:[0,1]
; __device__ __forceinline__ unsigned cvt_pk_bf16(float lo, float hi) { f32x2_t v = {lo, hi}; bf16x2_t b = __builtin_convertvector(v, bf16x2_t); return __builtin_bit_cast(unsigned, b); }
; __device__ __forceinline__ float fast_rcp(float x) { return __builtin_amdgcn_rcpf(x); }
;     template <int KIND>
;     __device__ __forceinline__ void run(const f32x4 (&acc)[2][2][4][2], const Unit& u, int wr, int wc, int fr, int fq) const {
;     ...
;             for (int ai = 0; ai < 2; ++ai)
; #pragma unroll
;                 for (int m = 0; m < 4; ++m) { const int row = row0 + ai * HALF + m * 16; const float a = __shfl(ai ? sa_hi : sa_lo, 16 * m + fr);
;                     const f32x4 f0 = __builtin_convertvector(__builtin_bit_cast(i32x4, acc[ai][bj][m][0]), f32x4), f1 = __builtin_convertvector(__builtin_bit_cast(i32x4, acc[ai][bj][m][1]), f32x4);
;                     f32x2_t v[4] = {(f32x2_t){f0[0], f0[1]}, (f32x2_t){f0[2], f0[3]}, (f32x2_t){f1[0], f1[1]}, (f32x2_t){f1[2], f1[3]}};
; #pragma unroll
;                     for (int j = 0; j < 4; ++j) {
;                         v[j] = v[j] * (sc2[j] * (f32x2_t){a, a});
;                         if (KIND == 0 || KIND == 1 || KIND == 3) {
;                             const f32x2_t e = v[j] * (f32x2_t){-LOG2E, -LOG2E};
;                             const f32x2_t dn = (f32x2_t){__builtin_amdgcn_exp2f(e[0]), __builtin_amdgcn_exp2f(e[1])} + (f32x2_t){1.0f, 1.0f};
;                             const f32x2_t sg = (f32x2_t){fast_rcp(dn[0]), fast_rcp(dn[1])};
;                             if (KIND == 0) v[j] = v[j] * sg;
;                             else if (KIND == 3) v[j] = (v[j] * sg) * aux2[j];
;                             else { const f32x2_t f = __builtin_elementwise_fma((f32x2_t){1.0f, 1.0f} - aux2[j], sg, aux2[j]);
;                                 v[j] = (f32x2_t){fmaxf(__logf(f[0]), -60.0f), fmaxf(__logf(f[1]), -60.0f)}; }
;                         }
;                     }
;                     u32x4 w; w.x = cvt_pk_bf16(v[0][0], v[0][1]); w.y = cvt_pk_bf16(v[1][0], v[1][1]); w.z = cvt_pk_bf16(v[2][0], v[2][1]); w.w = cvt_pk_bf16(v[3][0], v[3][1]);
;                     *(u32x4*)(O + (size_t)row * NPROJ + col0 + bj * HALF) = w; }
	v_pk_mul_f32 v[156:157], v[156:157], v[136:137]
	v_pk_mul_f32 v[136:137], v[168:169], v[134:135] op_sel_hi:[0,1]
	v_pk_mul_f32 v[152:153], v[152:153], v[136:137]
	v_cvt_pk_bf16_f32 v136, v138, v139
	v_cvt_pk_bf16_f32 v137, v158, v159
	v_cvt_pk_bf16_f32 v138, v156, v157
	v_cvt_pk_bf16_f32 v139, v152, v153
	global_store_dwordx4 v[178:179], v[136:139], off offset:256
	v_cvt_f32_i32_e32 v157, v27
	v_cvt_f32_i32_e32 v156, v26
	v_cvt_f32_i32_e32 v139, v31
	v_cvt_f32_i32_e32 v138, v30
	v_cvt_f32_i32_e32 v137, v33
	v_cvt_f32_i32_e32 v136, v32
	v_cvt_f32_i32_e32 v153, v29
	v_cvt_f32_i32_e32 v152, v28
	v_pk_mul_f32 v[158:159], v[170:171], v[162:163] op_sel_hi:[0,1]
	v_pk_mul_f32 v[138:139], v[138:139], v[158:159]
	v_pk_mul_f32 v[158:159], v[170:171], v[164:165] op_sel_hi:[0,1]
	v_pk_mul_f32 v[158:159], v[136:137], v[158:159]
	v_pk_mul_f32 v[136:137], v[170:171], v[132:133] op_sel_hi:[0,1]
	v_pk_mul_f32 v[156:157], v[156:157], v[136:137]
	v_pk_mul_f32 v[136:137], v[170:171], v[134:135] op_sel_hi:[0,1]
	v_pk_mul_f32 v[152:153], v[152:153], v[136:137]
	v_cvt_pk_bf16_f32 v136, v138, v139
	v_cvt_pk_bf16_f32 v137, v158, v159
	v_cvt_pk_bf16_f32 v138, v156, v157
	v_cvt_pk_bf16_f32 v139, v152, v153
	global_store_dwordx4 v[180:181], v[136:139], off offset:256
	v_cvt_f32_i32_e32 v157, v19
	v_cvt_f32_i32_e32 v156, v18
	v_cvt_f32_i32_e32 v139, v23
	v_cvt_f32_i32_e32 v138, v22
	v_cvt_f32_i32_e32 v137, v25
	v_cvt_f32_i32_e32 v136, v24
	v_cvt_f32_i32_e32 v153, v21
	v_cvt_f32_i32_e32 v152, v20
	v_pk_mul_f32 v[158:159], v[172:173], v[162:163] op_sel_hi:[0,1]
	v_pk_mul_f32 v[138:139], v[138:139], v[158:159]
	v_pk_mul_f32 v[158:159], v[172:173], v[164:165] op_sel_hi:[0,1]
	v_pk_mul_f32 v[158:159], v[136:137], v[158:159]
	v_pk_mul_f32 v[136:137], v[172:173], v[132:133] op_sel_hi:[0,1]
	v_pk_mul_f32 v[156:157], v[156:157], v[136:137]
	v_pk_mul_f32 v[136:137], v[172:173], v[134:135] op_sel_hi:[0,1]
	v_pk_mul_f32 v[152:153], v[152:153], v[136:137]
	v_cvt_pk_bf16_f32 v136, v138, v139
	v_cvt_pk_bf16_f32 v137, v158, v159
	v_cvt_pk_bf16_f32 v138, v156, v157
	v_cvt_pk_bf16_f32 v139, v152, v153
	global_store_dwordx4 v[182:183], v[136:139], off offset:256
	v_cvt_f32_i32_e32 v157, v11
	v_cvt_f32_i32_e32 v156, v10
	v_cvt_f32_i32_e32 v139, v15
	v_cvt_f32_i32_e32 v138, v14
	v_cvt_f32_i32_e32 v137, v17
	v_cvt_f32_i32_e32 v136, v16
	v_cvt_f32_i32_e32 v153, v13
	v_cvt_f32_i32_e32 v152, v12
	v_pk_mul_f32 v[158:159], v[174:175], v[162:163] op_sel_hi:[0,1]
	v_pk_mul_f32 v[138:139], v[138:139], v[158:159]
	v_pk_mul_f32 v[158:159], v[174:175], v[164:165] op_sel_hi:[0,1]
	v_pk_mul_f32 v[158:159], v[136:137], v[158:159]
	v_pk_mul_f32 v[136:137], v[174:175], v[132:133] op_sel_hi:[0,1]
	v_pk_mul_f32 v[156:157], v[156:157], v[136:137]
	v_pk_mul_f32 v[136:137], v[174:175], v[134:135] op_sel_hi:[0,1]
	v_pk_mul_f32 v[152:153], v[152:153], v[136:137]
	v_cvt_pk_bf16_f32 v136, v138, v139
	v_cvt_pk_bf16_f32 v137, v158, v159
	v_cvt_pk_bf16_f32 v138, v156, v157
	v_cvt_pk_bf16_f32 v139, v152, v153
	global_store_dwordx4 v[184:185], v[136:139], off offset:256
	v_cvt_f32_i32_e32 v153, v5
	v_cvt_f32_i32_e32 v152, v4
	v_cvt_f32_i32_e32 v137, v7
	v_cvt_f32_i32_e32 v136, v6
	v_cvt_f32_i32_e32 v139, v9
	v_cvt_f32_i32_e32 v138, v8
	v_cvt_f32_i32_e32 v157, v3
	v_cvt_f32_i32_e32 v156, v2
	v_pk_mul_f32 v[158:159], v[176:177], v[162:163] op_sel_hi:[0,1]
	v_pk_mul_f32 v[136:137], v[136:137], v[158:159]
	v_pk_mul_f32 v[158:159], v[176:177], v[164:165] op_sel_hi:[0,1]
	v_pk_mul_f32 v[132:133], v[176:177], v[132:133] op_sel_hi:[0,1]
	v_pk_mul_f32 v[134:135], v[176:177], v[134:135] op_sel_hi:[0,1]
	v_pk_mul_f32 v[138:139], v[138:139], v[158:159]
	v_pk_mul_f32 v[132:133], v[156:157], v[132:133]
	v_pk_mul_f32 v[134:135], v[152:153], v[134:135]

;     template <int KIND>
;     __device__ __forceinline__ void run(const f32x4 (&acc)[2][2][4][2], const Unit& u, int wr, int wc, int fr, int fq) const {
;         const int row0 = u.pm * BM + wr * 64 + fr, col0 = u.pn * BM + wc * 32 + 8 * fq;
;         const float sa_lo = sa[u.pm * BM + wr * 64 + fr + 16 * fq], sa_hi = sa[u.pm * BM + HALF + wr * 64 + fr + 16 * fq];
; #pragma unroll
;         for (int bj = 0; bj < 2; ++bj) {
;             f32x2_t sc2[4], aux2[4];
; #pragma unroll
;             for (int j = 0; j < 4; ++j) {
;                 const float k0 = (KIND == 4) ? (0.125f * LOG2E / 127.0f) : (1.0f / 127.0f);
;                 sc2[j] = (f32x2_t){wmax[col0 + bj * HALF + 2 * j] * k0, wmax[col0 + bj * HALF + 2 * j + 1] * k0};
;                 if (KIND == 1) aux2[j] = (f32x2_t){lb[col0 - C_HG + bj * HALF + 2 * j], lb[col0 - C_HG + bj * HALF + 2 * j + 1]};
;                 else if (KIND == 3) aux2[j] = (f32x2_t){gain[col0 - C_HGATE + bj * HALF + 2 * j], gain[col0 - C_HGATE + bj * HALF + 2 * j + 1]};
;                 else aux2[j] = (f32x2_t){0.f, 0.f};
;             }
; #pragma unroll
;             for (int ai = 0; ai < 2; ++ai)
; #pragma unroll
;                 for (int m = 0; m < 4; ++m) { const int row = row0 + ai * HALF + m * 16; const float a = __shfl(ai ? sa_hi : sa_lo, 16 * m + fr);
;                     const f32x4 f0 = __builtin_convertvector(__builtin_bit_cast(i32x4, acc[ai][bj][m][0]), f32x4), f1 = __builtin_convertvector(__builtin_bit_cast(i32x4, acc[ai][bj][m][1]), f32x4);
;                     f32x2_t v[4] = {(f32x2_t){f0[0], f0[1]}, (f32x2_t){f0[2], f0[3]}, (f32x2_t){f1[0], f1[1]}, (f32x2_t){f1[2], f1[3]}};
; #pragma unroll
;                     for (int j = 0; j < 4; ++j) {
;                         v[j] = v[j] * (sc2[j] * (f32x2_t){a, a});
;                         if (KIND == 0 || KIND == 1 || KIND == 3) {
;                             const f32x2_t e = v[j] * (f32x2_t){-LOG2E, -LOG2E};
;                             const f32x2_t dn = (f32x2_t){__builtin_amdgcn_exp2f(e[0]), __builtin_amdgcn_exp2f(e[1])} + (f32x2_t){1.0f, 1.0f};
;                             const f32x2_t sg = (f32x2_t){fast_rcp(dn[0]), fast_rcp(dn[1])};
;                             if (KIND == 0) v[j] = v[j] * sg;
;                             else if (KIND == 3) v[j] = (v[j] * sg) * aux2[j];
.LBB0_222:
	s_andn2_b64 vcc, exec, s[8:9]
	v_lshlrev_b32_e32 v210, 2, v233
	v_lshlrev_b64 v[152:153], 1, v[146:147]
	v_or_b32_e32 v163, 16, v175
	v_or_b32_e32 v177, 32, v175
	v_or_b32_e32 v187, 48, v175
	v_add_u32_e32 v169, 0x80, v175
	v_add_u32_e32 v186, 0x90, v175
	v_add_u32_e32 v211, 0xa0, v175
	v_add_u32_e32 v234, 0xb0, v175
	s_cbranch_vccnz .LBB0_224
	v_mov_b32_e32 v150, v242
	v_mov_b32_e32 v151, v243
	v_mov_b32_e32 v134, v238
	v_mov_b32_e32 v135, v239
	v_mov_b32_e32 v136, v240
	v_mov_b32_e32 v137, v241
	global_load_dwordx4 v[236:239], v[148:149], off offset:528
	global_load_dwordx4 v[240:243], v[148:149], off offset:512
	ds_bpermute_b32 v66, v210, v209
	s_mov_b32 s2, 0x3c010204
	v_cvt_f32_i32_e32 v157, v129
	v_cvt_f32_i32_e32 v156, v128
	v_pk_mul_f32 v[132:133], v[154:155], s[2:3] op_sel_hi:[1,0]
	v_cvt_f32_i32_e32 v161, v125
	v_cvt_f32_i32_e32 v160, v124
	v_cvt_f32_i32_e32 v159, v127
	v_cvt_f32_i32_e32 v158, v126
	s_waitcnt lgkmcnt(0)
	v_pk_mul_f32 v[164:165], v[132:133], v[66:67] op_sel_hi:[1,0]
	v_cvt_f32_i32_e32 v167, v119
	v_pk_mul_f32 v[156:157], v[156:157], v[164:165]
	v_cvt_f32_i32_e32 v166, v118
	v_cvt_pk_bf16_f32 v170, v156, v157
	ds_bpermute_b32 v156, v210, v209 offset:64
	ds_bpermute_b32 v162, v210, v209 offset:128
	ds_bpermute_b32 v168, v210, v209 offset:192
	v_cvt_f32_i32_e32 v183, v93
	v_cvt_f32_i32_e32 v182, v92
	v_cvt_f32_i32_e32 v189, v85
	s_waitcnt lgkmcnt(1)
	v_pk_mul_f32 v[178:179], v[132:133], v[162:163] op_sel_hi:[1,0]
	s_waitcnt lgkmcnt(0)
	v_pk_mul_f32 v[180:181], v[132:133], v[168:169] op_sel_hi:[1,0]
	v_cvt_f32_i32_e32 v188, v84
	ds_bpermute_b32 v174, v210, v208 offset:128
	ds_bpermute_b32 v176, v210, v208 offset:192
	s_waitcnt lgkmcnt(1)
	v_pk_mul_f32 v[192:193], v[132:133], v[174:175] op_sel_hi:[1,0]
	v_pk_mul_f32 v[138:139], v[134:135], s[2:3] op_sel_hi:[1,0]
	v_pk_mul_f32 v[134:135], v[150:151], s[2:3] op_sel_hi:[1,0]
	v_cvt_f32_i32_e32 v151, v131
	v_cvt_f32_i32_e32 v150, v130
	v_pk_mul_f32 v[136:137], v[136:137], s[2:3] op_sel_hi:[1,0]
	v_pk_mul_f32 v[164:165], v[138:139], v[66:67] op_sel_hi:[1,0]
	s_nop 0
	v_pk_mul_f32 v[150:151], v[150:151], v[164:165]
	v_pk_mul_f32 v[164:165], v[136:137], v[66:67] op_sel_hi:[1,0]
	v_cvt_pk_bf16_f32 v171, v150, v151
	v_pk_mul_f32 v[160:161], v[160:161], v[164:165]
	v_pk_mul_f32 v[164:165], v[134:135], v[66:67] op_sel_hi:[1,0]
	v_cvt_pk_bf16_f32 v172, v160, v161
	v_pk_mul_f32 v[158:159], v[158:159], v[164:165]
	v_mov_b64_e32 v[164:165], s[14:15]
	v_mad_i64_i32 v[150:151], s[0:1], v175, s81, v[164:165]
	v_cvt_f32_i32_e32 v161, v121
	v_cvt_f32_i32_e32 v160, v120
	v_cvt_pk_bf16_f32 v173, v158, v159
	v_lshl_add_u64 v[158:159], v[150:151], 0, v[152:153]
	v_cvt_f32_i32_e32 v151, v123
	v_cvt_f32_i32_e32 v150, v122
	global_store_dwordx4 v[158:159], v[170:173], off
	s_nop 1
	v_cvt_f32_i32_e32 v171, v117
	v_cvt_f32_i32_e32 v170, v116
	v_pk_mul_f32 v[172:173], v[132:133], v[156:157] op_sel_hi:[1,0]
	s_nop 0
	v_pk_mul_f32 v[160:161], v[160:161], v[172:173]
	v_pk_mul_f32 v[172:173], v[138:139], v[156:157] op_sel_hi:[1,0]
	s_nop 0
	v_pk_mul_f32 v[150:151], v[150:151], v[172:173]
	v_pk_mul_f32 v[172:173], v[136:137], v[156:157] op_sel_hi:[1,0]
	s_nop 0
	v_pk_mul_f32 v[172:173], v[170:171], v[172:173]
	v_pk_mul_f32 v[170:171], v[134:135], v[156:157] op_sel_hi:[1,0]
	v_cvt_pk_bf16_f32 v172, v172, v173
	v_pk_mul_f32 v[166:167], v[166:167], v[170:171]
	v_cvt_pk_bf16_f32 v171, v150, v151
	v_cvt_pk_bf16_f32 v173, v166, v167
	v_mad_i64_i32 v[150:151], s[0:1], v163, s81, v[164:165]
	v_cvt_f32_i32_e32 v167, v113
	v_cvt_f32_i32_e32 v166, v112
	v_cvt_pk_bf16_f32 v170, v160, v161
	v_lshl_add_u64 v[160:161], v[150:151], 0, v[152:153]
	v_cvt_f32_i32_e32 v151, v115
	v_cvt_f32_i32_e32 v150, v114
	global_store_dwordx4 v[160:161], v[170:173], off
	v_pk_mul_f32 v[166:167], v[166:167], v[178:179]
	v_pk_mul_f32 v[178:179], v[138:139], v[162:163] op_sel_hi:[1,0]
	v_cvt_f32_i32_e32 v173, v109
	v_cvt_f32_i32_e32 v172, v108
	v_cvt_f32_i32_e32 v171, v111
	v_cvt_f32_i32_e32 v170, v110
	v_pk_mul_f32 v[150:151], v[150:151], v[178:179]
	v_pk_mul_f32 v[178:179], v[136:137], v[162:163] op_sel_hi:[1,0]
	s_nop 0
	v_pk_mul_f32 v[172:173], v[172:173], v[178:179]
	v_pk_mul_f32 v[178:179], v[134:135], v[162:163] op_sel_hi:[1,0]
	v_cvt_pk_bf16_f32 v172, v172, v173
	v_pk_mul_f32 v[178:179], v[170:171], v[178:179]
	v_cvt_pk_bf16_f32 v171, v150, v151
	v_mad_i64_i32 v[150:151], s[0:1], v177, s81, v[164:165]
	v_cvt_pk_bf16_f32 v170, v166, v167
	v_cvt_pk_bf16_f32 v173, v178, v179
	v_lshl_add_u64 v[166:167], v[150:151], 0, v[152:153]
	global_store_dwordx4 v[166:167], v[170:173], off
	v_cvt_f32_i32_e32 v151, v107
	v_cvt_f32_i32_e32 v150, v106
	v_cvt_f32_i32_e32 v171, v105
	v_cvt_f32_i32_e32 v170, v104
	v_cvt_f32_i32_e32 v179, v101
	v_cvt_f32_i32_e32 v178, v100
	v_cvt_f32_i32_e32 v173, v103
	v_cvt_f32_i32_e32 v172, v102
	v_pk_mul_f32 v[170:171], v[170:171], v[180:181]
	v_pk_mul_f32 v[180:181], v[138:139], v[168:169] op_sel_hi:[1,0]
	v_cvt_pk_bf16_f32 v170, v170, v171
	v_pk_mul_f32 v[150:151], v[150:151], v[180:181]
	v_pk_mul_f32 v[180:181], v[136:137], v[168:169] op_sel_hi:[1,0]
	v_cvt_pk_bf16_f32 v171, v150, v151
	v_pk_mul_f32 v[178:179], v[178:179], v[180:181]
	v_pk_mul_f32 v[180:181], v[134:135], v[168:169] op_sel_hi:[1,0]
	v_mad_i64_i32 v[150:151], s[0:1], v187, s81, v[164:165]
	v_pk_mul_f32 v[180:181], v[172:173], v[180:181]
	v_cvt_pk_bf16_f32 v172, v178, v179
	v_cvt_pk_bf16_f32 v173, v180, v181
	v_lshl_add_u64 v[178:179], v[150:151], 0, v[152:153]
	global_store_dwordx4 v[178:179], v[170:173], off
	ds_bpermute_b32 v170, v210, v208
	v_cvt_f32_i32_e32 v151, v99
	v_cvt_f32_i32_e32 v173, v97
	v_cvt_f32_i32_e32 v172, v96
	v_cvt_f32_i32_e32 v150, v98
	v_cvt_f32_i32_e32 v181, v95
	v_cvt_f32_i32_e32 v180, v94
	s_waitcnt lgkmcnt(0)
; __device__ __forceinline__ unsigned cvt_pk_bf16(float lo, float hi) { f32x2_t v = {lo, hi}; bf16x2_t b = __builtin_convertvector(v, bf16x2_t); return __builtin_bit_cast(unsigned, b); }
; __device__ __forceinline__ float fast_rcp(float x) { return __builtin_amdgcn_rcpf(x); }
;     template <int KIND>
;     __device__ __forceinline__ void run(const f32x4 (&acc)[2][2][4][2], const Unit& u, int wr, int wc, int fr, int fq) const {
;     ...
;             for (int ai = 0; ai < 2; ++ai)
; #pragma unroll
;                 for (int m = 0; m < 4; ++m) { const int row = row0 + ai * HALF + m * 16; const float a = __shfl(ai ? sa_hi : sa_lo, 16 * m + fr);
;                     const f32x4 f0 = __builtin_convertvector(__builtin_bit_cast(i32x4, acc[ai][bj][m][0]), f32x4), f1 = __builtin_convertvector(__builtin_bit_cast(i32x4, acc[ai][bj][m][1]), f32x4);
;                     f32x2_t v[4] = {(f32x2_t){f0[0], f0[1]}, (f32x2_t){f0[2], f0[3]}, (f32x2_t){f1[0], f1[1]}, (f32x2_t){f1[2], f1[3]}};
; #pragma unroll
;                     for (int j = 0; j < 4; ++j) {
;                         v[j] = v[j] * (sc2[j] * (f32x2_t){a, a});
;                         if (KIND == 0 || KIND == 1 || KIND == 3) {
;                             const f32x2_t e = v[j] * (f32x2_t){-LOG2E, -LOG2E};
;                             const f32x2_t dn = (f32x2_t){__builtin_amdgcn_exp2f(e[0]), __builtin_amdgcn_exp2f(e[1])} + (f32x2_t){1.0f, 1.0f};
;                             const f32x2_t sg = (f32x2_t){fast_rcp(dn[0]), fast_rcp(dn[1])};
;                             if (KIND == 0) v[j] = v[j] * sg;
;                             else if (KIND == 3) v[j] = (v[j] * sg) * aux2[j];
;                             else { const f32x2_t f = __builtin_elementwise_fma((f32x2_t){1.0f, 1.0f} - aux2[j], sg, aux2[j]);
;                                 v[j] = (f32x2_t){fmaxf(__logf(f[0]), -60.0f), fmaxf(__logf(f[1]), -60.0f)}; }
;                         }
;                     }
;                     u32x4 w; w.x = cvt_pk_bf16(v[0][0], v[0][1]); w.y = cvt_pk_bf16(v[1][0], v[1][1]); w.z = cvt_pk_bf16(v[2][0], v[2][1]); w.w = cvt_pk_bf16(v[3][0], v[3][1]);
;                     *(u32x4*)(O + (size_t)row * NPROJ + col0 + bj * HALF) = w; }
	v_pk_mul_f32 v[184:185], v[132:133], v[170:171] op_sel_hi:[1,0]
	s_nop 0
	v_pk_mul_f32 v[172:173], v[172:173], v[184:185]
	v_pk_mul_f32 v[184:185], v[138:139], v[170:171] op_sel_hi:[1,0]
	s_nop 0
	v_pk_mul_f32 v[150:151], v[150:151], v[184:185]
	v_pk_mul_f32 v[184:185], v[136:137], v[170:171] op_sel_hi:[1,0]
	s_nop 0
	v_pk_mul_f32 v[184:185], v[182:183], v[184:185]
	v_pk_mul_f32 v[182:183], v[134:135], v[170:171] op_sel_hi:[1,0]
	v_cvt_pk_bf16_f32 v184, v184, v185
	v_pk_mul_f32 v[180:181], v[180:181], v[182:183]
	v_cvt_pk_bf16_f32 v182, v172, v173
	v_cvt_pk_bf16_f32 v183, v150, v151
	v_mad_i64_i32 v[150:151], s[0:1], v169, s81, v[164:165]
	ds_bpermute_b32 v172, v210, v208 offset:64
	v_cvt_pk_bf16_f32 v185, v180, v181
	v_lshl_add_u64 v[180:181], v[150:151], 0, v[152:153]
	global_store_dwordx4 v[180:181], v[182:185], off
	v_cvt_f32_i32_e32 v151, v91
	v_cvt_f32_i32_e32 v150, v90
	v_cvt_f32_i32_e32 v183, v89
	v_cvt_f32_i32_e32 v182, v88
	v_cvt_f32_i32_e32 v185, v87
	v_cvt_f32_i32_e32 v184, v86
	s_waitcnt lgkmcnt(0)
	v_pk_mul_f32 v[190:191], v[132:133], v[172:173] op_sel_hi:[1,0]
	v_pk_mul_f32 v[132:133], v[132:133], v[176:177] op_sel_hi:[1,0]
	v_pk_mul_f32 v[182:183], v[182:183], v[190:191]
	v_pk_mul_f32 v[190:191], v[138:139], v[172:173] op_sel_hi:[1,0]
	s_nop 0
	v_pk_mul_f32 v[150:151], v[150:151], v[190:191]
	v_pk_mul_f32 v[190:191], v[136:137], v[172:173] op_sel_hi:[1,0]
	s_nop 0
	v_pk_mul_f32 v[190:191], v[188:189], v[190:191]
	v_pk_mul_f32 v[188:189], v[134:135], v[172:173] op_sel_hi:[1,0]
	v_cvt_pk_bf16_f32 v190, v190, v191
	v_pk_mul_f32 v[184:185], v[184:185], v[188:189]
	v_cvt_pk_bf16_f32 v189, v150, v151
	v_cvt_pk_bf16_f32 v191, v184, v185
	v_mad_i64_i32 v[150:151], s[0:1], v186, s81, v[164:165]
	v_cvt_f32_i32_e32 v185, v81
	v_cvt_f32_i32_e32 v184, v80
	v_cvt_pk_bf16_f32 v188, v182, v183
	v_lshl_add_u64 v[182:183], v[150:151], 0, v[152:153]
	v_cvt_f32_i32_e32 v151, v83
	v_cvt_f32_i32_e32 v150, v82
	global_store_dwordx4 v[182:183], v[188:191], off
	v_pk_mul_f32 v[184:185], v[184:185], v[192:193]
	v_pk_mul_f32 v[192:193], v[138:139], v[174:175] op_sel_hi:[1,0]
	v_cvt_f32_i32_e32 v191, v77
	v_cvt_f32_i32_e32 v190, v76
	v_cvt_f32_i32_e32 v189, v79
	v_cvt_f32_i32_e32 v188, v78
	v_pk_mul_f32 v[150:151], v[150:151], v[192:193]
	v_pk_mul_f32 v[192:193], v[136:137], v[174:175] op_sel_hi:[1,0]
	v_pk_mul_f32 v[136:137], v[136:137], v[176:177] op_sel_hi:[1,0]
	v_pk_mul_f32 v[190:191], v[190:191], v[192:193]
	v_pk_mul_f32 v[192:193], v[134:135], v[174:175] op_sel_hi:[1,0]
	v_cvt_pk_bf16_f32 v190, v190, v191
	v_pk_mul_f32 v[192:193], v[188:189], v[192:193]
	v_cvt_pk_bf16_f32 v189, v150, v151
	v_mad_i64_i32 v[150:151], s[0:1], v211, s81, v[164:165]
	v_cvt_pk_bf16_f32 v188, v184, v185
	v_cvt_pk_bf16_f32 v191, v192, v193
	v_lshl_add_u64 v[184:185], v[150:151], 0, v[152:153]
	v_cvt_f32_i32_e32 v193, v69
	v_cvt_f32_i32_e32 v192, v68
	global_store_dwordx4 v[184:185], v[188:191], off
	v_cvt_f32_i32_e32 v151, v75
	v_cvt_f32_i32_e32 v150, v74
	v_cvt_f32_i32_e32 v189, v73
	v_cvt_f32_i32_e32 v188, v72
	v_cvt_f32_i32_e32 v191, v71
	v_cvt_f32_i32_e32 v190, v70
	v_pk_mul_f32 v[138:139], v[138:139], v[176:177] op_sel_hi:[1,0]
	v_pk_mul_f32 v[136:137], v[192:193], v[136:137]
	v_pk_mul_f32 v[134:135], v[134:135], v[176:177] op_sel_hi:[1,0]
	v_pk_mul_f32 v[132:133], v[188:189], v[132:133]
	v_pk_mul_f32 v[138:139], v[150:151], v[138:139]
	v_pk_mul_f32 v[150:151], v[190:191], v[134:135]
	v_cvt_pk_bf16_f32 v134, v136, v137
	v_mad_i64_i32 v[136:137], s[0:1], v234, s81, v[164:165]
	v_cvt_pk_bf16_f32 v132, v132, v133
	v_cvt_pk_bf16_f32 v133, v138, v139
	v_cvt_pk_bf16_f32 v135, v150, v151
	v_lshl_add_u64 v[136:137], v[136:137], 0, v[152:153]
	global_store_dwordx4 v[136:137], v[132:135], off
	s_nop 1
	s_waitcnt vmcnt(8)
	v_mov_b32_e32 v132, v236
	v_mov_b32_e32 v133, v237
	v_mov_b32_e32 v134, v238
	v_mov_b32_e32 v135, v239
	v_mov_b32_e32 v136, v240
	v_mov_b32_e32 v137, v241
	v_mov_b32_e32 v138, v242
	v_mov_b32_e32 v139, v243
	v_cvt_f32_i32_e32 v193, v59
	v_cvt_f32_i32_e32 v192, v58
	v_cvt_f32_i32_e32 v191, v61
	v_cvt_f32_i32_e32 v190, v60
	v_mad_i64_i32 v[150:151], s[0:1], v234, s81, 0
	s_mov_b64 s[0:1], 0
	v_pk_mul_f32 v[132:133], v[132:133], s[2:3] op_sel_hi:[1,0]
	v_pk_mul_f32 v[188:189], v[138:139], s[2:3] op_sel_hi:[1,0]
	v_cvt_f32_i32_e32 v139, v63
	v_cvt_f32_i32_e32 v138, v62
	v_pk_mul_f32 v[164:165], v[136:137], s[2:3] op_sel_hi:[1,0]
	v_cvt_f32_i32_e32 v137, v65
	v_cvt_f32_i32_e32 v136, v64
	v_pk_mul_f32 v[194:195], v[66:67], v[164:165] op_sel_hi:[0,1]
	v_pk_mul_f32 v[138:139], v[138:139], v[194:195]
	v_pk_mul_f32 v[194:195], v[66:67], v[188:189] op_sel_hi:[0,1]
	v_pk_mul_f32 v[134:135], v[134:135], s[2:3] op_sel_hi:[1,0]
	v_pk_mul_f32 v[194:195], v[136:137], v[194:195]
	v_pk_mul_f32 v[136:137], v[66:67], v[132:133] op_sel_hi:[0,1]
	v_pk_mul_f32 v[192:193], v[192:193], v[136:137]
	v_pk_mul_f32 v[136:137], v[66:67], v[134:135] op_sel_hi:[0,1]
	v_pk_mul_f32 v[190:191], v[190:191], v[136:137]
	v_cvt_pk_bf16_f32 v136, v138, v139
	v_cvt_pk_bf16_f32 v137, v194, v195
	v_cvt_pk_bf16_f32 v138, v192, v193
	v_cvt_pk_bf16_f32 v139, v190, v191
	global_store_dwordx4 v[158:159], v[136:139], off offset:256
	v_cvt_f32_i32_e32 v191, v51
	v_cvt_f32_i32_e32 v190, v50
	v_cvt_f32_i32_e32 v139, v55
	v_cvt_f32_i32_e32 v138, v54
	v_cvt_f32_i32_e32 v137, v57
	v_cvt_f32_i32_e32 v136, v56
	v_cvt_f32_i32_e32 v159, v53
	v_cvt_f32_i32_e32 v158, v52
	v_pk_mul_f32 v[192:193], v[156:157], v[164:165] op_sel_hi:[0,1]
	v_pk_mul_f32 v[138:139], v[138:139], v[192:193]
	v_pk_mul_f32 v[192:193], v[156:157], v[188:189] op_sel_hi:[0,1]
	v_pk_mul_f32 v[192:193], v[136:137], v[192:193]
; __device__ __forceinline__ unsigned cvt_pk_bf16(float lo, float hi) { f32x2_t v = {lo, hi}; bf16x2_t b = __builtin_convertvector(v, bf16x2_t); return __builtin_bit_cast(unsigned, b); }
; __device__ __forceinline__ float fast_rcp(float x) { return __builtin_amdgcn_rcpf(x); }
;     template <int KIND>
;     __device__ __forceinline__ void run(const f32x4 (&acc)[2][2][4][2], const Unit& u, int wr, int wc, int fr, int fq) const {
;     ...
;             for (int ai = 0; ai < 2; ++ai)
; #pragma unroll
;                 for (int m = 0; m < 4; ++m) { const int row = row0 + ai * HALF + m * 16; const float a = __shfl(ai ? sa_hi : sa_lo, 16 * m + fr);
;                     const f32x4 f0 = __builtin_convertvector(__builtin_bit_cast(i32x4, acc[ai][bj][m][0]), f32x4), f1 = __builtin_convertvector(__builtin_bit_cast(i32x4, acc[ai][bj][m][1]), f32x4);
;                     f32x2_t v[4] = {(f32x2_t){f0[0], f0[1]}, (f32x2_t){f0[2], f0[3]}, (f32x2_t){f1[0], f1[1]}, (f32x2_t){f1[2], f1[3]}};
; #pragma unroll
;                     for (int j = 0; j < 4; ++j) {
;                         v[j] = v[j] * (sc2[j] * (f32x2_t){a, a});
;                         if (KIND == 0 || KIND == 1 || KIND == 3) {
;                             const f32x2_t e = v[j] * (f32x2_t){-LOG2E, -LOG2E};
;                             const f32x2_t dn = (f32x2_t){__builtin_amdgcn_exp2f(e[0]), __builtin_amdgcn_exp2f(e[1])} + (f32x2_t){1.0f, 1.0f};
;                             const f32x2_t sg = (f32x2_t){fast_rcp(dn[0]), fast_rcp(dn[1])};
;                             if (KIND == 0) v[j] = v[j] * sg;
;                             else if (KIND == 3) v[j] = (v[j] * sg) * aux2[j];
;                             else { const f32x2_t f = __builtin_elementwise_fma((f32x2_t){1.0f, 1.0f} - aux2[j], sg, aux2[j]);
;                                 v[j] = (f32x2_t){fmaxf(__logf(f[0]), -60.0f), fmaxf(__logf(f[1]), -60.0f)}; }
;                         }
;                     }
;                     u32x4 w; w.x = cvt_pk_bf16(v[0][0], v[0][1]); w.y = cvt_pk_bf16(v[1][0], v[1][1]); w.z = cvt_pk_bf16(v[2][0], v[2][1]); w.w = cvt_pk_bf16(v[3][0], v[3][1]);
;                     *(u32x4*)(O + (size_t)row * NPROJ + col0 + bj * HALF) = w; }
	v_pk_mul_f32 v[136:137], v[156:157], v[132:133] op_sel_hi:[0,1]
	v_pk_mul_f32 v[190:191], v[190:191], v[136:137]
	v_pk_mul_f32 v[136:137], v[156:157], v[134:135] op_sel_hi:[0,1]
	v_pk_mul_f32 v[156:157], v[158:159], v[136:137]
	v_cvt_pk_bf16_f32 v136, v138, v139
	v_cvt_pk_bf16_f32 v137, v192, v193
	v_cvt_pk_bf16_f32 v138, v190, v191
	v_cvt_pk_bf16_f32 v139, v156, v157
	global_store_dwordx4 v[160:161], v[136:139], off offset:256
	v_cvt_f32_i32_e32 v159, v43
	v_cvt_f32_i32_e32 v158, v42
	v_cvt_f32_i32_e32 v139, v47
	v_cvt_f32_i32_e32 v138, v46
	v_cvt_f32_i32_e32 v137, v49
	v_cvt_f32_i32_e32 v136, v48
	v_cvt_f32_i32_e32 v157, v45
	v_cvt_f32_i32_e32 v156, v44
	v_pk_mul_f32 v[160:161], v[162:163], v[164:165] op_sel_hi:[0,1]
	v_pk_mul_f32 v[138:139], v[138:139], v[160:161]
	v_pk_mul_f32 v[160:161], v[162:163], v[188:189] op_sel_hi:[0,1]
	v_pk_mul_f32 v[160:161], v[136:137], v[160:161]
	v_pk_mul_f32 v[136:137], v[162:163], v[132:133] op_sel_hi:[0,1]
	v_pk_mul_f32 v[158:159], v[158:159], v[136:137]
	v_pk_mul_f32 v[136:137], v[162:163], v[134:135] op_sel_hi:[0,1]
	v_pk_mul_f32 v[156:157], v[156:157], v[136:137]
	v_cvt_pk_bf16_f32 v136, v138, v139
	v_cvt_pk_bf16_f32 v137, v160, v161
	v_cvt_pk_bf16_f32 v138, v158, v159
	v_cvt_pk_bf16_f32 v139, v156, v157
	global_store_dwordx4 v[166:167], v[136:139], off offset:256
	v_cvt_f32_i32_e32 v159, v35
	v_cvt_f32_i32_e32 v158, v34
	v_cvt_f32_i32_e32 v139, v39
	v_cvt_f32_i32_e32 v138, v38
	v_cvt_f32_i32_e32 v137, v41
	v_cvt_f32_i32_e32 v136, v40
	v_cvt_f32_i32_e32 v157, v37
	v_cvt_f32_i32_e32 v156, v36
	v_pk_mul_f32 v[160:161], v[168:169], v[164:165] op_sel_hi:[0,1]
	v_pk_mul_f32 v[138:139], v[138:139], v[160:161]
	v_pk_mul_f32 v[160:161], v[168:169], v[188:189] op_sel_hi:[0,1]
	v_pk_mul_f32 v[160:161], v[136:137], v[160:161]
	v_pk_mul_f32 v[136:137], v[168:169], v[132:133] op_sel_hi:[0,1]
	v_pk_mul_f32 v[158:159], v[158:159], v[136:137]
	v_pk_mul_f32 v[136:137], v[168:169], v[134:135] op_sel_hi:[0,1]
	v_pk_mul_f32 v[156:157], v[156:157], v[136:137]
	v_cvt_pk_bf16_f32 v136, v138, v139
	v_cvt_pk_bf16_f32 v137, v160, v161
	v_cvt_pk_bf16_f32 v138, v158, v159
	v_cvt_pk_bf16_f32 v139, v156, v157
	global_store_dwordx4 v[178:179], v[136:139], off offset:256
	v_cvt_f32_i32_e32 v159, v27
	v_cvt_f32_i32_e32 v158, v26
	v_cvt_f32_i32_e32 v139, v31
	v_cvt_f32_i32_e32 v138, v30
	v_cvt_f32_i32_e32 v137, v33
	v_cvt_f32_i32_e32 v136, v32
	v_cvt_f32_i32_e32 v157, v29
	v_cvt_f32_i32_e32 v156, v28
	v_pk_mul_f32 v[160:161], v[170:171], v[164:165] op_sel_hi:[0,1]
	v_pk_mul_f32 v[138:139], v[138:139], v[160:161]
	v_pk_mul_f32 v[160:161], v[170:171], v[188:189] op_sel_hi:[0,1]
	v_pk_mul_f32 v[160:161], v[136:137], v[160:161]
	v_pk_mul_f32 v[136:137], v[170:171], v[132:133] op_sel_hi:[0,1]
	v_pk_mul_f32 v[158:159], v[158:159], v[136:137]
	v_pk_mul_f32 v[136:137], v[170:171], v[134:135] op_sel_hi:[0,1]
	v_pk_mul_f32 v[156:157], v[156:157], v[136:137]
	v_cvt_pk_bf16_f32 v136, v138, v139
	v_cvt_pk_bf16_f32 v137, v160, v161
	v_cvt_pk_bf16_f32 v138, v158, v159
	v_cvt_pk_bf16_f32 v139, v156, v157
	global_store_dwordx4 v[180:181], v[136:139], off offset:256
	v_cvt_f32_i32_e32 v159, v19
	v_cvt_f32_i32_e32 v158, v18
	v_cvt_f32_i32_e32 v139, v23
	v_cvt_f32_i32_e32 v138, v22
	v_cvt_f32_i32_e32 v137, v25
	v_cvt_f32_i32_e32 v136, v24
	v_cvt_f32_i32_e32 v157, v21
	v_cvt_f32_i32_e32 v156, v20
	v_pk_mul_f32 v[160:161], v[172:173], v[164:165] op_sel_hi:[0,1]
	v_pk_mul_f32 v[138:139], v[138:139], v[160:161]
	v_pk_mul_f32 v[160:161], v[172:173], v[188:189] op_sel_hi:[0,1]
	v_pk_mul_f32 v[160:161], v[136:137], v[160:161]
	v_pk_mul_f32 v[136:137], v[172:173], v[132:133] op_sel_hi:[0,1]
	v_pk_mul_f32 v[158:159], v[158:159], v[136:137]
	v_pk_mul_f32 v[136:137], v[172:173], v[134:135] op_sel_hi:[0,1]
	v_pk_mul_f32 v[156:157], v[156:157], v[136:137]
	v_cvt_pk_bf16_f32 v136, v138, v139
	v_cvt_pk_bf16_f32 v137, v160, v161
	v_cvt_pk_bf16_f32 v138, v158, v159
	v_cvt_pk_bf16_f32 v139, v156, v157
	global_store_dwordx4 v[182:183], v[136:139], off offset:256
	v_cvt_f32_i32_e32 v159, v11
	v_cvt_f32_i32_e32 v158, v10
	v_cvt_f32_i32_e32 v139, v15
	v_cvt_f32_i32_e32 v138, v14
	v_cvt_f32_i32_e32 v137, v17
	v_cvt_f32_i32_e32 v136, v16
	v_cvt_f32_i32_e32 v157, v13
	v_cvt_f32_i32_e32 v156, v12
	v_pk_mul_f32 v[160:161], v[174:175], v[164:165] op_sel_hi:[0,1]
	v_pk_mul_f32 v[138:139], v[138:139], v[160:161]
	v_pk_mul_f32 v[160:161], v[174:175], v[188:189] op_sel_hi:[0,1]
	v_pk_mul_f32 v[160:161], v[136:137], v[160:161]
	v_pk_mul_f32 v[136:137], v[174:175], v[132:133] op_sel_hi:[0,1]
	v_pk_mul_f32 v[158:159], v[158:159], v[136:137]
	v_pk_mul_f32 v[136:137], v[174:175], v[134:135] op_sel_hi:[0,1]
	v_pk_mul_f32 v[156:157], v[156:157], v[136:137]
	v_cvt_pk_bf16_f32 v136, v138, v139
	v_cvt_pk_bf16_f32 v137, v160, v161
	v_cvt_pk_bf16_f32 v138, v158, v159
	v_cvt_pk_bf16_f32 v139, v156, v157
	global_store_dwordx4 v[184:185], v[136:139], off offset:256
	v_cvt_f32_i32_e32 v157, v5
	v_cvt_f32_i32_e32 v156, v4
	v_cvt_f32_i32_e32 v137, v7
	v_cvt_f32_i32_e32 v136, v6
	v_cvt_f32_i32_e32 v139, v9
	v_cvt_f32_i32_e32 v138, v8
	v_cvt_f32_i32_e32 v159, v3
	v_cvt_f32_i32_e32 v158, v2
	v_pk_mul_f32 v[160:161], v[176:177], v[164:165] op_sel_hi:[0,1]
	v_pk_mul_f32 v[136:137], v[136:137], v[160:161]
	v_pk_mul_f32 v[160:161], v[176:177], v[188:189] op_sel_hi:[0,1]
	v_pk_mul_f32 v[132:133], v[176:177], v[132:133] op_sel_hi:[0,1]
	v_pk_mul_f32 v[134:135], v[176:177], v[134:135] op_sel_hi:[0,1]
	v_pk_mul_f32 v[138:139], v[138:139], v[160:161]
	v_pk_mul_f32 v[132:133], v[158:159], v[132:133]
	v_pk_mul_f32 v[134:135], v[156:157], v[134:135]
